# EpiResid: pair 8-byte fragment stores into 16-byte stores via v_permlane16_swap (half the store line requests), counted waits recomputed
# speedup vs baseline: 1.0173x; 1.0060x over previous
; __device__ __forceinline__ unsigned cvt_pk_bf16(float lo, float hi) { unsigned r; asm volatile("v_cvt_pk_bf16_f32 %0, %1, %2" : "=v"(r) : "v"(lo), "v"(hi)); return r; }
;     __device__ __forceinline__ void operator()(f32x4 (&acc)[2][2][4][2], const Unit& u, int wr, int wc, int fr, int fq) const {
;         const int col0 = u.pn * BM + wc * 32 + 4 * fq;
; #pragma unroll
;         for (int ai = 0; ai < 2; ++ai) {
;             unsigned long long old[4][2][2];
; #pragma unroll
;             for (int m = 0; m < 4; ++m) { const size_t off = (size_t)(u.pm * BM + ai * HALF + wr * 64 + m * 16 + fr) * ldc + col0;
; #pragma unroll
;                 for (int bj = 0; bj < 2; ++bj)
; #pragma unroll
;                     for (int n = 0; n < 2; ++n) old[m][bj][n] = *(const unsigned long long*)(xb + off + bj * HALF + n * 16); }
; #pragma unroll
;             for (int m = 0; m < 4; ++m) { const int row = u.pm * BM + ai * HALF + wr * 64 + m * 16 + fr; const size_t off = (size_t)row * ldc + col0; float sq = 0.f;
; #pragma unroll
;                 for (int bj = 0; bj < 2; ++bj)
; #pragma unroll
;                     for (int n = 0; n < 2; ++n) { const unsigned long long b = old[m][bj][n];
;                         const unsigned blo = (unsigned)b, bhi = (unsigned)(b >> 32);
;                         f32x4 v; v[0] = __builtin_bit_cast(float, blo << 16); v[1] = __builtin_bit_cast(float, blo & 0xffff0000u); v[2] = __builtin_bit_cast(float, bhi << 16); v[3] = __builtin_bit_cast(float, bhi & 0xffff0000u);
;                         v = v + acc[ai][bj][m][n];
;                         sq += (v[0] * v[0] + v[1] * v[1]) + (v[2] * v[2] + v[3] * v[3]);
;                         *(unsigned long long*)(xb + off + bj * HALF + n * 16) = (unsigned long long)cvt_pk_bf16(v[0], v[1]) | ((unsigned long long)cvt_pk_bf16(v[2], v[3]) << 32); }
;                 sq += __shfl_xor(sq, 16); sq += __shfl_xor(sq, 32);
;                 if (fq == 0) ssp[(size_t)row * 16 + 4 * u.pn + wc] = sq; }
.LBB0_1039:
	v_bfe_u32 v200, v229, 4, 1
	v_mul_u32_u24_e32 v200, 24, v200
	v_mov_b32_e32 v201, 0
	v_lshl_or_b32 v136, s12, 8, v174
	v_lshl_add_u32 v140, s13, 8, v172
	v_ashrrev_i32_e32 v137, 31, v136
	v_lshlrev_b64 v[176:177], 1, v[136:137]
	v_ashrrev_i32_e32 v141, 31, v140
	v_lshl_add_u64 v[138:139], s[42:43], 0, v[176:177]
	v_lshlrev_b64 v[178:179], 11, v[140:141]
	v_lshl_add_u64 v[142:143], v[138:139], 0, v[178:179]
	global_load_dwordx2 v[180:181], v[142:143], off
	global_load_dwordx2 v[182:183], v[142:143], off offset:32
	global_load_dwordx2 v[184:185], v[142:143], off offset:256
	global_load_dwordx2 v[188:189], v[142:143], off offset:288
	v_or_b32_e32 v160, 16, v140
	v_ashrrev_i32_e32 v161, 31, v160
	v_lshlrev_b64 v[142:143], 11, v[160:161]
	v_or_b32_e32 v146, 32, v140
	v_lshl_add_u64 v[142:143], v[138:139], 0, v[142:143]
	v_ashrrev_i32_e32 v147, 31, v146
	global_load_dwordx2 v[170:171], v[142:143], off
	global_load_dwordx2 v[168:169], v[142:143], off offset:32
	global_load_dwordx2 v[166:167], v[142:143], off offset:256
	global_load_dwordx2 v[164:165], v[142:143], off offset:288
	v_lshlrev_b64 v[142:143], 11, v[146:147]
	v_lshl_add_u64 v[142:143], v[138:139], 0, v[142:143]
	global_load_dwordx2 v[162:163], v[142:143], off
	global_load_dwordx2 v[158:159], v[142:143], off offset:32
	global_load_dwordx2 v[154:155], v[142:143], off offset:256
	global_load_dwordx2 v[150:151], v[142:143], off offset:288
	v_or_b32_e32 v142, 48, v140
	v_ashrrev_i32_e32 v143, 31, v142
	v_lshlrev_b64 v[144:145], 11, v[142:143]
	v_lshl_add_u64 v[144:145], v[138:139], 0, v[144:145]
	global_load_dwordx2 v[156:157], v[144:145], off
	global_load_dwordx2 v[152:153], v[144:145], off offset:32
	global_load_dwordx2 v[148:149], v[144:145], off offset:256
	s_nop 0
	global_load_dwordx2 v[144:145], v[144:145], off offset:288
	s_lshl_b32 s78, s12, 2
	s_ashr_i32 s79, s78, 31
	s_waitcnt vmcnt(0)
	s_mov_b32 s100, 1
	v_lshlrev_b32_e32 v190, 16, v180
	v_and_b32_e32 v191, 0xffff0000, v180
	v_lshlrev_b32_e32 v180, 16, v181
	v_and_b32_e32 v181, 0xffff0000, v181
	v_pk_add_f32 v[128:129], v[128:129], v[180:181]
	v_pk_add_f32 v[126:127], v[126:127], v[190:191]
	v_mul_f32_e32 v181, v129, v129
	v_mul_f32_e32 v180, v127, v127
	v_fmac_f32_e32 v180, v126, v126
	v_fmac_f32_e32 v181, v128, v128
	v_cvt_pk_bf16_f32 v126, v126, v127
	v_cvt_pk_bf16_f32 v127, v128, v129
	v_lshl_add_u64 v[128:129], s[42:43], 0, v[178:179]
	v_lshl_add_u64 v[128:129], v[128:129], 0, v[176:177]
	v_lshl_add_u64 v[128:129], v[128:129], 0, v[200:201]
	v_mov_b32_e32 v192, v126
	v_mov_b32_e32 v193, v127
	v_lshlrev_b32_e32 v126, 16, v182
	v_and_b32_e32 v127, 0xffff0000, v182
	v_pk_add_f32 v[122:123], v[122:123], v[126:127]
	v_lshlrev_b32_e32 v176, 16, v183
	v_and_b32_e32 v177, 0xffff0000, v183
	v_mul_f32_e32 v126, v123, v123
	v_pk_add_f32 v[124:125], v[124:125], v[176:177]
	v_fmac_f32_e32 v126, v122, v122
	v_cvt_pk_bf16_f32 v122, v122, v123
	v_cvt_pk_bf16_f32 v123, v124, v125
	v_mul_f32_e32 v127, v125, v125
	v_mov_b32_e32 v194, v122
	v_mov_b32_e32 v195, v123
	s_nop 1
	v_permlane16_swap_b32_e32 v192, v194
	v_permlane16_swap_b32_e32 v193, v195
	global_store_dwordx4 v[128:129], v[192:195], off
	v_lshlrev_b32_e32 v122, 16, v184
	v_and_b32_e32 v123, 0xffff0000, v184
	v_fmac_f32_e32 v127, v124, v124
	v_lshlrev_b32_e32 v124, 16, v185
	v_and_b32_e32 v125, 0xffff0000, v185
	v_pk_add_f32 v[118:119], v[118:119], v[122:123]
	v_pk_add_f32 v[120:121], v[120:121], v[124:125]
	v_mul_f32_e32 v122, v119, v119
	v_fmac_f32_e32 v122, v118, v118
	v_mul_f32_e32 v123, v121, v121
	v_cvt_pk_bf16_f32 v118, v118, v119
	v_cvt_pk_bf16_f32 v119, v120, v121
	v_fmac_f32_e32 v123, v120, v120
	v_mov_b32_e32 v196, v118
	v_mov_b32_e32 v197, v119
	v_lshlrev_b32_e32 v118, 16, v188
	v_and_b32_e32 v119, 0xffff0000, v188
	v_lshlrev_b32_e32 v120, 16, v189
	v_and_b32_e32 v121, 0xffff0000, v189
	v_pk_add_f32 v[116:117], v[116:117], v[120:121]
	v_pk_add_f32 v[118:119], v[114:115], v[118:119]
	v_add_f32_e32 v180, v180, v181
	v_add_f32_e32 v126, v126, v127
	v_mul_f32_e32 v114, v119, v119
	v_mul_f32_e32 v115, v117, v117
	v_add_f32_e32 v126, v180, v126
	v_add_f32_e32 v122, v122, v123
	v_fmac_f32_e32 v114, v118, v118
	v_fmac_f32_e32 v115, v116, v116
	v_add_f32_e32 v122, v126, v122
	v_add_f32_e32 v114, v114, v115
	v_cvt_pk_bf16_f32 v118, v118, v119
	v_cvt_pk_bf16_f32 v119, v116, v117
	v_and_b32_e32 v116, 64, v229
	v_add_f32_e32 v115, v122, v114
	v_xor_b32_e32 v114, 16, v229
	v_add_u32_e32 v117, 64, v116
	v_cmp_lt_i32_e32 vcc, v114, v117
	v_mov_b32_e32 v198, v118
	v_mov_b32_e32 v199, v119
	s_nop 1
	v_permlane16_swap_b32_e32 v196, v198
	v_permlane16_swap_b32_e32 v197, v199
	global_store_dwordx4 v[128:129], v[196:199], off offset:256
	s_nop 0
	v_cndmask_b32_e32 v114, v229, v114, vcc
	v_lshlrev_b32_e32 v114, 2, v114
	v_mov_b32_e32 v116, v115
	s_nop 1
	v_permlane16_swap_b32_e32 v116, v115
	s_waitcnt lgkmcnt(0)
	v_add_f32_e32 v116, v115, v116
	v_xor_b32_e32 v115, 32, v229
	v_cmp_lt_i32_e32 vcc, v115, v117
	s_nop 1
	v_cndmask_b32_e32 v115, v229, v115, vcc
	v_lshlrev_b32_e32 v115, 2, v115
	ds_bpermute_b32 v117, v115, v116
	s_and_saveexec_b64 s[80:81], s[6:7]
	s_cbranch_execz .LBB0_1041
	v_readlane_b32 s12, v253, 40
	v_lshlrev_b64 v[118:119], 6, v[140:141]
	v_readlane_b32 s13, v253, 41
	s_lshl_b32 s64, s90, 2
	s_waitcnt lgkmcnt(0)
	v_add_f32_e32 v116, v116, v117
	v_lshl_add_u64 v[118:119], s[12:13], 0, v[118:119]
	v_lshl_add_u64 v[118:119], s[78:79], 2, v[118:119]
	v_lshl_add_u64 v[118:119], v[118:119], 0, s[64:65]
	global_store_dword v[118:119], v116, off
; __device__ __forceinline__ unsigned cvt_pk_bf16(float lo, float hi) { unsigned r; asm volatile("v_cvt_pk_bf16_f32 %0, %1, %2" : "=v"(r) : "v"(lo), "v"(hi)); return r; }
;     __device__ __forceinline__ void operator()(f32x4 (&acc)[2][2][4][2], const Unit& u, int wr, int wc, int fr, int fq) const {
;         const int col0 = u.pn * BM + wc * 32 + 4 * fq;
; #pragma unroll
;         for (int ai = 0; ai < 2; ++ai) {
;             unsigned long long old[4][2][2];
; #pragma unroll
;             for (int m = 0; m < 4; ++m) { const size_t off = (size_t)(u.pm * BM + ai * HALF + wr * 64 + m * 16 + fr) * ldc + col0;
; #pragma unroll
;                 for (int bj = 0; bj < 2; ++bj)
; #pragma unroll
;                     for (int n = 0; n < 2; ++n) old[m][bj][n] = *(const unsigned long long*)(xb + off + bj * HALF + n * 16); }
; #pragma unroll
;             for (int m = 0; m < 4; ++m) { const int row = u.pm * BM + ai * HALF + wr * 64 + m * 16 + fr; const size_t off = (size_t)row * ldc + col0; float sq = 0.f;
; #pragma unroll
;                 for (int bj = 0; bj < 2; ++bj)
; #pragma unroll
;                     for (int n = 0; n < 2; ++n) { const unsigned long long b = old[m][bj][n];
;                         const unsigned blo = (unsigned)b, bhi = (unsigned)(b >> 32);
;                         f32x4 v; v[0] = __builtin_bit_cast(float, blo << 16); v[1] = __builtin_bit_cast(float, blo & 0xffff0000u); v[2] = __builtin_bit_cast(float, bhi << 16); v[3] = __builtin_bit_cast(float, bhi & 0xffff0000u);
;                         v = v + acc[ai][bj][m][n];
;                         sq += (v[0] * v[0] + v[1] * v[1]) + (v[2] * v[2] + v[3] * v[3]);
;                         *(unsigned long long*)(xb + off + bj * HALF + n * 16) = (unsigned long long)cvt_pk_bf16(v[0], v[1]) | ((unsigned long long)cvt_pk_bf16(v[2], v[3]) << 32); }
;                 sq += __shfl_xor(sq, 16); sq += __shfl_xor(sq, 32);
;                 if (fq == 0) ssp[(size_t)row * 16 + 4 * u.pn + wc] = sq; }
.LBB0_1041:
	s_or_b64 exec, exec, s[80:81]
	v_lshlrev_b32_e32 v118, 16, v170
	v_and_b32_e32 v119, 0xffff0000, v170
	v_lshlrev_b32_e32 v120, 16, v171
	v_and_b32_e32 v121, 0xffff0000, v171
	v_pk_add_f32 v[112:113], v[112:113], v[120:121]
	v_pk_add_f32 v[110:111], v[110:111], v[118:119]
	s_waitcnt lgkmcnt(0)
	v_lshlrev_b64 v[116:117], 10, v[160:161]
	v_mul_f32_e32 v118, v111, v111
	v_mul_f32_e32 v119, v113, v113
	v_fmac_f32_e32 v118, v110, v110
	v_fmac_f32_e32 v119, v112, v112
	v_cvt_pk_bf16_f32 v110, v110, v111
	v_cvt_pk_bf16_f32 v111, v112, v113
	v_lshl_add_u64 v[112:113], v[116:117], 1, s[42:43]
	v_lshl_add_u64 v[112:113], v[136:137], 1, v[112:113]
	v_lshl_add_u64 v[112:113], v[112:113], 0, v[200:201]
	v_mov_b32_e32 v192, v110
	v_mov_b32_e32 v193, v111
	v_lshlrev_b32_e32 v110, 16, v168
	v_and_b32_e32 v111, 0xffff0000, v168
	v_lshlrev_b32_e32 v116, 16, v169
	v_and_b32_e32 v117, 0xffff0000, v169
	v_pk_add_f32 v[108:109], v[108:109], v[116:117]
	v_pk_add_f32 v[106:107], v[106:107], v[110:111]
	v_mul_f32_e32 v111, v109, v109
	v_mul_f32_e32 v110, v107, v107
	v_fmac_f32_e32 v110, v106, v106
	v_fmac_f32_e32 v111, v108, v108
	v_add_f32_e32 v118, v118, v119
	v_add_f32_e32 v110, v110, v111
	v_add_f32_e32 v118, v118, v110
	v_lshlrev_b32_e32 v110, 16, v166
	v_and_b32_e32 v111, 0xffff0000, v166
	v_lshlrev_b32_e32 v116, 16, v167
	v_and_b32_e32 v117, 0xffff0000, v167
	v_pk_add_f32 v[104:105], v[104:105], v[116:117]
	v_pk_add_f32 v[102:103], v[102:103], v[110:111]
	v_cvt_pk_bf16_f32 v106, v106, v107
	v_mul_f32_e32 v110, v105, v105
	v_mul_f32_e32 v107, v103, v103
	v_fmac_f32_e32 v107, v102, v102
	v_fmac_f32_e32 v110, v104, v104
	v_add_f32_e32 v107, v107, v110
	v_lshlrev_b32_e32 v110, 16, v164
	v_and_b32_e32 v111, 0xffff0000, v164
	v_lshlrev_b32_e32 v116, 16, v165
	v_and_b32_e32 v117, 0xffff0000, v165
	v_pk_add_f32 v[100:101], v[100:101], v[116:117]
	v_pk_add_f32 v[110:111], v[98:99], v[110:111]
	v_mul_f32_e32 v99, v101, v101
	v_mul_f32_e32 v98, v111, v111
	v_fmac_f32_e32 v98, v110, v110
	v_fmac_f32_e32 v99, v100, v100
	v_add_f32_e32 v107, v118, v107
	v_add_f32_e32 v98, v98, v99
	v_add_f32_e32 v98, v107, v98
	v_mov_b32_e32 v99, v98
	s_nop 1
	v_permlane16_swap_b32_e32 v99, v98
	v_cvt_pk_bf16_f32 v107, v108, v109
	v_mov_b32_e32 v194, v106
	v_mov_b32_e32 v195, v107
	s_nop 1
	v_permlane16_swap_b32_e32 v192, v194
	v_permlane16_swap_b32_e32 v193, v195
	global_store_dwordx4 v[112:113], v[192:195], off
	v_cvt_pk_bf16_f32 v102, v102, v103
	v_cvt_pk_bf16_f32 v103, v104, v105
	s_waitcnt lgkmcnt(0)
	v_add_f32_e32 v98, v98, v99
	ds_bpermute_b32 v99, v115, v98
	v_mov_b32_e32 v196, v102
	v_mov_b32_e32 v197, v103
	v_cvt_pk_bf16_f32 v102, v110, v111
	v_cvt_pk_bf16_f32 v103, v100, v101
	v_mov_b32_e32 v198, v102
	v_mov_b32_e32 v199, v103
	s_nop 1
	v_permlane16_swap_b32_e32 v196, v198
	v_permlane16_swap_b32_e32 v197, v199
	global_store_dwordx4 v[112:113], v[196:199], off offset:256
	s_and_saveexec_b64 s[80:81], s[6:7]
	s_cbranch_execz .LBB0_1043
	v_readlane_b32 s12, v253, 40
	v_lshlrev_b64 v[100:101], 6, v[160:161]
	v_readlane_b32 s13, v253, 41
	s_lshl_b32 s64, s90, 2
	s_waitcnt lgkmcnt(0)
	v_add_f32_e32 v98, v98, v99
	v_lshl_add_u64 v[100:101], s[12:13], 0, v[100:101]
	v_lshl_add_u64 v[100:101], s[78:79], 2, v[100:101]
	v_lshl_add_u64 v[100:101], v[100:101], 0, s[64:65]
	global_store_dword v[100:101], v98, off
.LBB0_1043:
	s_or_b64 exec, exec, s[80:81]
	v_lshlrev_b32_e32 v100, 16, v162
	v_and_b32_e32 v101, 0xffff0000, v162
	v_lshlrev_b32_e32 v102, 16, v163
	v_and_b32_e32 v103, 0xffff0000, v163
	v_pk_add_f32 v[96:97], v[96:97], v[102:103]
	v_pk_add_f32 v[94:95], v[94:95], v[100:101]
	s_waitcnt lgkmcnt(0)
	v_lshlrev_b64 v[98:99], 10, v[146:147]
	v_mul_f32_e32 v100, v95, v95
	v_mul_f32_e32 v101, v97, v97
	v_fmac_f32_e32 v100, v94, v94
	v_fmac_f32_e32 v101, v96, v96
	v_cvt_pk_bf16_f32 v94, v94, v95
	v_cvt_pk_bf16_f32 v95, v96, v97
	v_lshl_add_u64 v[96:97], v[98:99], 1, s[42:43]
	v_lshl_add_u64 v[96:97], v[136:137], 1, v[96:97]
	v_lshl_add_u64 v[96:97], v[96:97], 0, v[200:201]
	v_mov_b32_e32 v192, v94
	v_mov_b32_e32 v193, v95
	v_lshlrev_b32_e32 v94, 16, v158
	v_and_b32_e32 v95, 0xffff0000, v158
	v_lshlrev_b32_e32 v98, 16, v159
	v_and_b32_e32 v99, 0xffff0000, v159
	v_pk_add_f32 v[92:93], v[92:93], v[98:99]
	v_pk_add_f32 v[90:91], v[90:91], v[94:95]
	v_mul_f32_e32 v95, v93, v93
	v_mul_f32_e32 v94, v91, v91
	v_fmac_f32_e32 v94, v90, v90
	v_fmac_f32_e32 v95, v92, v92
	v_add_f32_e32 v100, v100, v101
	v_add_f32_e32 v94, v94, v95
	v_add_f32_e32 v100, v100, v94
	v_lshlrev_b32_e32 v94, 16, v154
	v_and_b32_e32 v95, 0xffff0000, v154
	v_lshlrev_b32_e32 v98, 16, v155
	v_and_b32_e32 v99, 0xffff0000, v155
	v_pk_add_f32 v[88:89], v[88:89], v[98:99]
	v_pk_add_f32 v[86:87], v[86:87], v[94:95]
	v_cvt_pk_bf16_f32 v90, v90, v91
	v_mul_f32_e32 v94, v89, v89
	v_mul_f32_e32 v91, v87, v87
	v_fmac_f32_e32 v91, v86, v86
	v_fmac_f32_e32 v94, v88, v88
	v_add_f32_e32 v91, v91, v94
	v_lshlrev_b32_e32 v94, 16, v150
	v_and_b32_e32 v95, 0xffff0000, v150
	v_lshlrev_b32_e32 v98, 16, v151
	v_and_b32_e32 v99, 0xffff0000, v151
	v_pk_add_f32 v[84:85], v[84:85], v[98:99]
	v_pk_add_f32 v[94:95], v[82:83], v[94:95]
	v_mul_f32_e32 v83, v85, v85
	v_mul_f32_e32 v82, v95, v95
	v_fmac_f32_e32 v82, v94, v94
	v_fmac_f32_e32 v83, v84, v84
	v_add_f32_e32 v91, v100, v91
	v_add_f32_e32 v82, v82, v83
	v_add_f32_e32 v82, v91, v82
	v_mov_b32_e32 v83, v82
	s_nop 1
	v_permlane16_swap_b32_e32 v83, v82
	v_cvt_pk_bf16_f32 v91, v92, v93
	v_mov_b32_e32 v194, v90
	v_mov_b32_e32 v195, v91
	s_nop 1
	v_permlane16_swap_b32_e32 v192, v194
	v_permlane16_swap_b32_e32 v193, v195
	global_store_dwordx4 v[96:97], v[192:195], off
	v_cvt_pk_bf16_f32 v86, v86, v87
	v_cvt_pk_bf16_f32 v87, v88, v89
	s_waitcnt lgkmcnt(0)
	v_add_f32_e32 v82, v82, v83
	ds_bpermute_b32 v83, v115, v82
	v_mov_b32_e32 v196, v86
	v_mov_b32_e32 v197, v87
	v_cvt_pk_bf16_f32 v86, v94, v95
	v_cvt_pk_bf16_f32 v87, v84, v85
	v_mov_b32_e32 v198, v86
	v_mov_b32_e32 v199, v87
	s_nop 1
	v_permlane16_swap_b32_e32 v196, v198
	v_permlane16_swap_b32_e32 v197, v199
	global_store_dwordx4 v[96:97], v[196:199], off offset:256
	s_and_saveexec_b64 s[80:81], s[6:7]
	v_readlane_b32 s85, v255, 27
	s_cbranch_execz .LBB0_1045
	v_readlane_b32 s12, v253, 40
	v_lshlrev_b64 v[84:85], 6, v[146:147]
	v_readlane_b32 s13, v253, 41
	s_lshl_b32 s64, s90, 2
	s_waitcnt lgkmcnt(0)
	v_add_f32_e32 v82, v82, v83
	v_lshl_add_u64 v[84:85], s[12:13], 0, v[84:85]
	v_lshl_add_u64 v[84:85], s[78:79], 2, v[84:85]
	v_lshl_add_u64 v[84:85], v[84:85], 0, s[64:65]
	global_store_dword v[84:85], v82, off
; __device__ __forceinline__ unsigned cvt_pk_bf16(float lo, float hi) { unsigned r; asm volatile("v_cvt_pk_bf16_f32 %0, %1, %2" : "=v"(r) : "v"(lo), "v"(hi)); return r; }
;     __device__ __forceinline__ void operator()(f32x4 (&acc)[2][2][4][2], const Unit& u, int wr, int wc, int fr, int fq) const {
;     ...
;             for (int m = 0; m < 4; ++m) { const size_t off = (size_t)(u.pm * BM + ai * HALF + wr * 64 + m * 16 + fr) * ldc + col0;
; #pragma unroll
;                 for (int bj = 0; bj < 2; ++bj)
; #pragma unroll
;                     for (int n = 0; n < 2; ++n) old[m][bj][n] = *(const unsigned long long*)(xb + off + bj * HALF + n * 16); }
; #pragma unroll
;             for (int m = 0; m < 4; ++m) { const int row = u.pm * BM + ai * HALF + wr * 64 + m * 16 + fr; const size_t off = (size_t)row * ldc + col0; float sq = 0.f;
; #pragma unroll
;                 for (int bj = 0; bj < 2; ++bj)
; #pragma unroll
;                     for (int n = 0; n < 2; ++n) { const unsigned long long b = old[m][bj][n];
;                         const unsigned blo = (unsigned)b, bhi = (unsigned)(b >> 32);
;                         f32x4 v; v[0] = __builtin_bit_cast(float, blo << 16); v[1] = __builtin_bit_cast(float, blo & 0xffff0000u); v[2] = __builtin_bit_cast(float, bhi << 16); v[3] = __builtin_bit_cast(float, bhi & 0xffff0000u);
;                         v = v + acc[ai][bj][m][n];
;                         sq += (v[0] * v[0] + v[1] * v[1]) + (v[2] * v[2] + v[3] * v[3]);
;                         *(unsigned long long*)(xb + off + bj * HALF + n * 16) = (unsigned long long)cvt_pk_bf16(v[0], v[1]) | ((unsigned long long)cvt_pk_bf16(v[2], v[3]) << 32); }
;                 sq += __shfl_xor(sq, 16); sq += __shfl_xor(sq, 32);
;                 if (fq == 0) ssp[(size_t)row * 16 + 4 * u.pn + wc] = sq; }
.LBB0_1045:
	s_or_b64 exec, exec, s[80:81]
	v_lshlrev_b32_e32 v84, 16, v156
	v_and_b32_e32 v85, 0xffff0000, v156
	v_lshlrev_b32_e32 v86, 16, v157
	v_and_b32_e32 v87, 0xffff0000, v157
	v_pk_add_f32 v[80:81], v[80:81], v[86:87]
	v_pk_add_f32 v[78:79], v[78:79], v[84:85]
	s_waitcnt lgkmcnt(0)
	v_lshlrev_b64 v[82:83], 10, v[142:143]
	v_mul_f32_e32 v84, v79, v79
	v_mul_f32_e32 v85, v81, v81
	v_fmac_f32_e32 v84, v78, v78
	v_fmac_f32_e32 v85, v80, v80
	v_cvt_pk_bf16_f32 v78, v78, v79
	v_cvt_pk_bf16_f32 v79, v80, v81
	v_lshl_add_u64 v[80:81], v[82:83], 1, s[42:43]
	v_lshl_add_u64 v[80:81], v[136:137], 1, v[80:81]
	v_lshl_add_u64 v[80:81], v[80:81], 0, v[200:201]
	v_mov_b32_e32 v192, v78
	v_mov_b32_e32 v193, v79
	v_lshlrev_b32_e32 v78, 16, v152
	v_and_b32_e32 v79, 0xffff0000, v152
	v_lshlrev_b32_e32 v82, 16, v153
	v_and_b32_e32 v83, 0xffff0000, v153
	v_pk_add_f32 v[76:77], v[76:77], v[82:83]
	v_pk_add_f32 v[74:75], v[74:75], v[78:79]
	v_mul_f32_e32 v79, v77, v77
	v_mul_f32_e32 v78, v75, v75
	v_fmac_f32_e32 v78, v74, v74
	v_fmac_f32_e32 v79, v76, v76
	v_add_f32_e32 v84, v84, v85
	v_add_f32_e32 v78, v78, v79
	v_add_f32_e32 v84, v84, v78
	v_lshlrev_b32_e32 v78, 16, v148
	v_and_b32_e32 v79, 0xffff0000, v148
	v_lshlrev_b32_e32 v82, 16, v149
	v_and_b32_e32 v83, 0xffff0000, v149
	v_pk_add_f32 v[72:73], v[72:73], v[82:83]
	v_pk_add_f32 v[70:71], v[70:71], v[78:79]
	v_cvt_pk_bf16_f32 v74, v74, v75
	v_mul_f32_e32 v78, v73, v73
	v_mul_f32_e32 v75, v71, v71
	v_fmac_f32_e32 v75, v70, v70
	v_fmac_f32_e32 v78, v72, v72
	v_add_f32_e32 v75, v75, v78
	v_lshlrev_b32_e32 v78, 16, v144
	v_and_b32_e32 v79, 0xffff0000, v144
	v_lshlrev_b32_e32 v82, 16, v145
	v_and_b32_e32 v83, 0xffff0000, v145
	v_pk_add_f32 v[68:69], v[68:69], v[82:83]
	v_pk_add_f32 v[78:79], v[66:67], v[78:79]
	v_mul_f32_e32 v67, v69, v69
	v_mul_f32_e32 v66, v79, v79
	v_fmac_f32_e32 v66, v78, v78
	v_fmac_f32_e32 v67, v68, v68
	v_add_f32_e32 v75, v84, v75
	v_add_f32_e32 v66, v66, v67
	v_add_f32_e32 v66, v75, v66
	v_mov_b32_e32 v67, v66
	s_nop 1
	v_permlane16_swap_b32_e32 v67, v66
	v_cvt_pk_bf16_f32 v75, v76, v77
	v_mov_b32_e32 v194, v74
	v_mov_b32_e32 v195, v75
	s_nop 1
	v_permlane16_swap_b32_e32 v192, v194
	v_permlane16_swap_b32_e32 v193, v195
	global_store_dwordx4 v[80:81], v[192:195], off
	v_cvt_pk_bf16_f32 v70, v70, v71
	v_cvt_pk_bf16_f32 v71, v72, v73
	s_waitcnt lgkmcnt(0)
	v_add_f32_e32 v66, v66, v67
	ds_bpermute_b32 v67, v115, v66
	v_mov_b32_e32 v196, v70
	v_mov_b32_e32 v197, v71
	v_cvt_pk_bf16_f32 v70, v78, v79
	v_cvt_pk_bf16_f32 v71, v68, v69
	v_mov_b32_e32 v198, v70
	v_mov_b32_e32 v199, v71
	s_nop 1
	v_permlane16_swap_b32_e32 v196, v198
	v_permlane16_swap_b32_e32 v197, v199
	global_store_dwordx4 v[80:81], v[196:199], off offset:256
	s_and_saveexec_b64 s[80:81], s[6:7]
	s_cbranch_execz .LBB0_1047
	v_readlane_b32 s12, v253, 40
	v_lshlrev_b64 v[68:69], 6, v[142:143]
	v_readlane_b32 s13, v253, 41
	s_lshl_b32 s64, s90, 2
	s_waitcnt lgkmcnt(0)
	v_add_f32_e32 v66, v66, v67
	v_lshl_add_u64 v[68:69], s[12:13], 0, v[68:69]
	v_lshl_add_u64 v[68:69], s[78:79], 2, v[68:69]
	v_lshl_add_u64 v[68:69], v[68:69], 0, s[64:65]
	global_store_dword v[68:69], v66, off
.LBB0_1047:
	s_or_b64 exec, exec, s[80:81]
	v_add_u32_e32 v96, 0x80, v140
	v_ashrrev_i32_e32 v97, 31, v96
	v_lshlrev_b64 v[102:103], 11, v[96:97]
	s_waitcnt lgkmcnt(0)
	v_lshl_add_u64 v[66:67], v[138:139], 0, v[102:103]
	global_load_dwordx2 v[104:105], v[66:67], off
	global_load_dwordx2 v[106:107], v[66:67], off offset:32
	global_load_dwordx2 v[100:101], v[66:67], off offset:256
	global_load_dwordx2 v[98:99], v[66:67], off offset:288
	v_add_u32_e32 v84, 0x90, v140
	v_ashrrev_i32_e32 v85, 31, v84
	v_lshlrev_b64 v[66:67], 11, v[84:85]
	v_add_u32_e32 v70, 0xa0, v140
	v_lshl_add_u64 v[66:67], v[138:139], 0, v[66:67]
	v_ashrrev_i32_e32 v71, 31, v70
	global_load_dwordx2 v[94:95], v[66:67], off
	global_load_dwordx2 v[92:93], v[66:67], off offset:32
	global_load_dwordx2 v[90:91], v[66:67], off offset:256
	global_load_dwordx2 v[88:89], v[66:67], off offset:288
	v_lshlrev_b64 v[66:67], 11, v[70:71]
	v_lshl_add_u64 v[66:67], v[138:139], 0, v[66:67]
	global_load_dwordx2 v[86:87], v[66:67], off
	global_load_dwordx2 v[82:83], v[66:67], off offset:32
	global_load_dwordx2 v[78:79], v[66:67], off offset:256
	global_load_dwordx2 v[74:75], v[66:67], off offset:288
	v_add_u32_e32 v66, 0xb0, v140
	v_ashrrev_i32_e32 v67, 31, v66
	v_lshlrev_b64 v[68:69], 11, v[66:67]
	v_lshl_add_u64 v[68:69], v[138:139], 0, v[68:69]
	global_load_dwordx2 v[80:81], v[68:69], off
	global_load_dwordx2 v[76:77], v[68:69], off offset:32
	global_load_dwordx2 v[72:73], v[68:69], off offset:256
	s_nop 0
	global_load_dwordx2 v[68:69], v[68:69], off offset:288
	s_waitcnt vmcnt(15)
	v_lshlrev_b32_e32 v108, 16, v104
	v_and_b32_e32 v109, 0xffff0000, v104
	v_lshlrev_b32_e32 v104, 16, v105
	v_and_b32_e32 v105, 0xffff0000, v105
	v_pk_add_f32 v[64:65], v[64:65], v[104:105]
	v_pk_add_f32 v[62:63], v[62:63], v[108:109]
	v_mul_f32_e32 v105, v65, v65
	v_mul_f32_e32 v104, v63, v63
	v_fmac_f32_e32 v104, v62, v62
	v_fmac_f32_e32 v105, v64, v64
	v_add_f32_e32 v108, v104, v105
	v_cvt_pk_bf16_f32 v104, v62, v63
	v_cvt_pk_bf16_f32 v105, v64, v65
	s_waitcnt vmcnt(14)
	v_lshlrev_b32_e32 v64, 16, v106
	v_and_b32_e32 v65, 0xffff0000, v106
	v_lshl_add_u64 v[62:63], s[42:43], 0, v[102:103]
	v_pk_add_f32 v[58:59], v[58:59], v[64:65]
	v_lshl_add_u64 v[62:63], v[136:137], 1, v[62:63]
	v_lshlrev_b32_e32 v102, 16, v107
	v_and_b32_e32 v103, 0xffff0000, v107
	v_mul_f32_e32 v64, v59, v59
	v_lshl_add_u64 v[62:63], v[62:63], 0, v[200:201]
	v_mov_b32_e32 v192, v104
	v_mov_b32_e32 v193, v105
	v_pk_add_f32 v[60:61], v[60:61], v[102:103]
	v_fmac_f32_e32 v64, v58, v58
	v_cvt_pk_bf16_f32 v58, v58, v59
	v_cvt_pk_bf16_f32 v59, v60, v61
	v_mul_f32_e32 v65, v61, v61
	v_mov_b32_e32 v194, v58
	v_mov_b32_e32 v195, v59
	s_nop 1
	v_permlane16_swap_b32_e32 v192, v194
	v_permlane16_swap_b32_e32 v193, v195
	global_store_dwordx4 v[62:63], v[192:195], off
	s_waitcnt vmcnt(14)
; __device__ __forceinline__ unsigned cvt_pk_bf16(float lo, float hi) { unsigned r; asm volatile("v_cvt_pk_bf16_f32 %0, %1, %2" : "=v"(r) : "v"(lo), "v"(hi)); return r; }
;     __device__ __forceinline__ void operator()(f32x4 (&acc)[2][2][4][2], const Unit& u, int wr, int wc, int fr, int fq) const {
;     ...
;             for (int m = 0; m < 4; ++m) { const int row = u.pm * BM + ai * HALF + wr * 64 + m * 16 + fr; const size_t off = (size_t)row * ldc + col0; float sq = 0.f;
; #pragma unroll
;                 for (int bj = 0; bj < 2; ++bj)
; #pragma unroll
;                     for (int n = 0; n < 2; ++n) { const unsigned long long b = old[m][bj][n];
;                         const unsigned blo = (unsigned)b, bhi = (unsigned)(b >> 32);
;                         f32x4 v; v[0] = __builtin_bit_cast(float, blo << 16); v[1] = __builtin_bit_cast(float, blo & 0xffff0000u); v[2] = __builtin_bit_cast(float, bhi << 16); v[3] = __builtin_bit_cast(float, bhi & 0xffff0000u);
;                         v = v + acc[ai][bj][m][n];
;                         sq += (v[0] * v[0] + v[1] * v[1]) + (v[2] * v[2] + v[3] * v[3]);
;                         *(unsigned long long*)(xb + off + bj * HALF + n * 16) = (unsigned long long)cvt_pk_bf16(v[0], v[1]) | ((unsigned long long)cvt_pk_bf16(v[2], v[3]) << 32); }
;                 sq += __shfl_xor(sq, 16); sq += __shfl_xor(sq, 32);
;                 if (fq == 0) ssp[(size_t)row * 16 + 4 * u.pn + wc] = sq; }
	v_lshlrev_b32_e32 v58, 16, v100
	v_and_b32_e32 v59, 0xffff0000, v100
	v_fmac_f32_e32 v65, v60, v60
	v_lshlrev_b32_e32 v60, 16, v101
	v_and_b32_e32 v61, 0xffff0000, v101
	v_pk_add_f32 v[54:55], v[54:55], v[58:59]
	v_pk_add_f32 v[56:57], v[56:57], v[60:61]
	v_mul_f32_e32 v58, v55, v55
	v_fmac_f32_e32 v58, v54, v54
	v_mul_f32_e32 v59, v57, v57
	v_cvt_pk_bf16_f32 v54, v54, v55
	v_cvt_pk_bf16_f32 v55, v56, v57
	v_fmac_f32_e32 v59, v56, v56
	v_mov_b32_e32 v196, v54
	v_mov_b32_e32 v197, v55
	s_waitcnt vmcnt(13)
	v_lshlrev_b32_e32 v54, 16, v98
	v_and_b32_e32 v55, 0xffff0000, v98
	v_lshlrev_b32_e32 v56, 16, v99
	v_and_b32_e32 v57, 0xffff0000, v99
	v_pk_add_f32 v[52:53], v[52:53], v[56:57]
	v_pk_add_f32 v[50:51], v[50:51], v[54:55]
	v_add_f32_e32 v64, v64, v65
	v_mul_f32_e32 v54, v51, v51
	v_mul_f32_e32 v55, v53, v53
	v_add_f32_e32 v64, v108, v64
	v_add_f32_e32 v58, v58, v59
	v_fmac_f32_e32 v54, v50, v50
	v_fmac_f32_e32 v55, v52, v52
	v_add_f32_e32 v58, v64, v58
	v_add_f32_e32 v54, v54, v55
	v_add_f32_e32 v54, v58, v54
	v_cvt_pk_bf16_f32 v50, v50, v51
	v_cvt_pk_bf16_f32 v51, v52, v53
	v_mov_b32_e32 v198, v50
	v_mov_b32_e32 v199, v51
	s_nop 1
	v_permlane16_swap_b32_e32 v196, v198
	v_permlane16_swap_b32_e32 v197, v199
	global_store_dwordx4 v[62:63], v[196:199], off offset:256
	ds_bpermute_b32 v50, v114, v54
	s_waitcnt lgkmcnt(0)
	v_add_f32_e32 v50, v54, v50
	ds_bpermute_b32 v51, v115, v50
	s_and_saveexec_b64 s[80:81], s[6:7]
	s_cbranch_execz .LBB0_1049
	v_readlane_b32 s12, v253, 40
	v_lshlrev_b64 v[52:53], 6, v[96:97]
	v_readlane_b32 s13, v253, 41
	s_lshl_b32 s64, s90, 2
	s_waitcnt lgkmcnt(0)
	v_add_f32_e32 v50, v50, v51
	v_lshl_add_u64 v[52:53], s[12:13], 0, v[52:53]
	v_lshl_add_u64 v[52:53], s[78:79], 2, v[52:53]
	v_lshl_add_u64 v[52:53], v[52:53], 0, s[64:65]
	global_store_dword v[52:53], v50, off
.LBB0_1049:
	s_or_b64 exec, exec, s[80:81]
	s_waitcnt vmcnt(13)
	v_lshlrev_b32_e32 v52, 16, v94
	v_and_b32_e32 v53, 0xffff0000, v94
	v_lshlrev_b32_e32 v54, 16, v95
	v_and_b32_e32 v55, 0xffff0000, v95
	v_pk_add_f32 v[48:49], v[48:49], v[54:55]
	v_pk_add_f32 v[46:47], v[46:47], v[52:53]
	s_waitcnt lgkmcnt(0)
	v_lshlrev_b64 v[50:51], 10, v[84:85]
	v_mul_f32_e32 v52, v47, v47
	v_mul_f32_e32 v53, v49, v49
	v_fmac_f32_e32 v52, v46, v46
	v_fmac_f32_e32 v53, v48, v48
	v_cvt_pk_bf16_f32 v46, v46, v47
	v_cvt_pk_bf16_f32 v47, v48, v49
	v_lshl_add_u64 v[48:49], v[50:51], 1, s[42:43]
	v_lshl_add_u64 v[48:49], v[136:137], 1, v[48:49]
	v_lshl_add_u64 v[48:49], v[48:49], 0, v[200:201]
	v_mov_b32_e32 v192, v46
	v_mov_b32_e32 v193, v47
	s_waitcnt vmcnt(12)
	v_lshlrev_b32_e32 v46, 16, v92
	v_and_b32_e32 v47, 0xffff0000, v92
	v_lshlrev_b32_e32 v50, 16, v93
	v_and_b32_e32 v51, 0xffff0000, v93
	v_pk_add_f32 v[44:45], v[44:45], v[50:51]
	v_pk_add_f32 v[42:43], v[42:43], v[46:47]
	v_mul_f32_e32 v47, v45, v45
	v_mul_f32_e32 v46, v43, v43
	v_fmac_f32_e32 v46, v42, v42
	v_fmac_f32_e32 v47, v44, v44
	v_add_f32_e32 v52, v52, v53
	v_add_f32_e32 v46, v46, v47
	v_add_f32_e32 v52, v52, v46
	s_waitcnt vmcnt(11)
	v_lshlrev_b32_e32 v46, 16, v90
	v_and_b32_e32 v47, 0xffff0000, v90
	v_lshlrev_b32_e32 v50, 16, v91
	v_and_b32_e32 v51, 0xffff0000, v91
	v_pk_add_f32 v[40:41], v[40:41], v[50:51]
	v_pk_add_f32 v[38:39], v[38:39], v[46:47]
	v_cvt_pk_bf16_f32 v42, v42, v43
	v_mul_f32_e32 v46, v41, v41
	v_mul_f32_e32 v43, v39, v39
	v_fmac_f32_e32 v43, v38, v38
	v_fmac_f32_e32 v46, v40, v40
	v_add_f32_e32 v43, v43, v46
	s_waitcnt vmcnt(10)
	v_lshlrev_b32_e32 v46, 16, v88
	v_and_b32_e32 v47, 0xffff0000, v88
	v_lshlrev_b32_e32 v50, 16, v89
	v_and_b32_e32 v51, 0xffff0000, v89
	v_pk_add_f32 v[36:37], v[36:37], v[50:51]
	v_pk_add_f32 v[46:47], v[34:35], v[46:47]
	v_mul_f32_e32 v35, v37, v37
	v_mul_f32_e32 v34, v47, v47
	v_fmac_f32_e32 v34, v46, v46
	v_fmac_f32_e32 v35, v36, v36
	v_add_f32_e32 v43, v52, v43
	v_add_f32_e32 v34, v34, v35
	v_add_f32_e32 v34, v43, v34
	v_mov_b32_e32 v35, v34
	s_nop 1
	v_permlane16_swap_b32_e32 v35, v34
	v_cvt_pk_bf16_f32 v43, v44, v45
	v_mov_b32_e32 v194, v42
	v_mov_b32_e32 v195, v43
	s_nop 1
	v_permlane16_swap_b32_e32 v192, v194
	v_permlane16_swap_b32_e32 v193, v195
	global_store_dwordx4 v[48:49], v[192:195], off
	v_cvt_pk_bf16_f32 v38, v38, v39
	v_cvt_pk_bf16_f32 v39, v40, v41
	s_waitcnt lgkmcnt(0)
	v_add_f32_e32 v34, v34, v35
	ds_bpermute_b32 v35, v115, v34
	v_mov_b32_e32 v196, v38
	v_mov_b32_e32 v197, v39
	v_cvt_pk_bf16_f32 v38, v46, v47
	v_cvt_pk_bf16_f32 v39, v36, v37
	v_mov_b32_e32 v198, v38
	v_mov_b32_e32 v199, v39
	s_nop 1
	v_permlane16_swap_b32_e32 v196, v198
	v_permlane16_swap_b32_e32 v197, v199
	global_store_dwordx4 v[48:49], v[196:199], off offset:256
	s_and_saveexec_b64 s[80:81], s[6:7]
	s_cbranch_execz .LBB0_1051
	v_readlane_b32 s12, v253, 40
	v_lshlrev_b64 v[36:37], 6, v[84:85]
	v_readlane_b32 s13, v253, 41
	s_lshl_b32 s64, s90, 2
	s_waitcnt lgkmcnt(0)
	v_add_f32_e32 v34, v34, v35
	v_lshl_add_u64 v[36:37], s[12:13], 0, v[36:37]
	v_lshl_add_u64 v[36:37], s[78:79], 2, v[36:37]
	v_lshl_add_u64 v[36:37], v[36:37], 0, s[64:65]
	global_store_dword v[36:37], v34, off
; __device__ __forceinline__ unsigned cvt_pk_bf16(float lo, float hi) { unsigned r; asm volatile("v_cvt_pk_bf16_f32 %0, %1, %2" : "=v"(r) : "v"(lo), "v"(hi)); return r; }
;     __device__ __forceinline__ void operator()(f32x4 (&acc)[2][2][4][2], const Unit& u, int wr, int wc, int fr, int fq) const {
;     ...
;             for (int m = 0; m < 4; ++m) { const int row = u.pm * BM + ai * HALF + wr * 64 + m * 16 + fr; const size_t off = (size_t)row * ldc + col0; float sq = 0.f;
; #pragma unroll
;                 for (int bj = 0; bj < 2; ++bj)
; #pragma unroll
;                     for (int n = 0; n < 2; ++n) { const unsigned long long b = old[m][bj][n];
;                         const unsigned blo = (unsigned)b, bhi = (unsigned)(b >> 32);
;                         f32x4 v; v[0] = __builtin_bit_cast(float, blo << 16); v[1] = __builtin_bit_cast(float, blo & 0xffff0000u); v[2] = __builtin_bit_cast(float, bhi << 16); v[3] = __builtin_bit_cast(float, bhi & 0xffff0000u);
;                         v = v + acc[ai][bj][m][n];
;                         sq += (v[0] * v[0] + v[1] * v[1]) + (v[2] * v[2] + v[3] * v[3]);
;                         *(unsigned long long*)(xb + off + bj * HALF + n * 16) = (unsigned long long)cvt_pk_bf16(v[0], v[1]) | ((unsigned long long)cvt_pk_bf16(v[2], v[3]) << 32); }
;                 sq += __shfl_xor(sq, 16); sq += __shfl_xor(sq, 32);
;                 if (fq == 0) ssp[(size_t)row * 16 + 4 * u.pn + wc] = sq; }
.LBB0_1051:
	s_or_b64 exec, exec, s[80:81]
	s_waitcnt vmcnt(11)
	v_lshlrev_b32_e32 v36, 16, v86
	v_and_b32_e32 v37, 0xffff0000, v86
	v_lshlrev_b32_e32 v38, 16, v87
	v_and_b32_e32 v39, 0xffff0000, v87
	v_pk_add_f32 v[32:33], v[32:33], v[38:39]
	v_pk_add_f32 v[30:31], v[30:31], v[36:37]
	s_waitcnt lgkmcnt(0)
	v_lshlrev_b64 v[34:35], 10, v[70:71]
	v_mul_f32_e32 v36, v31, v31
	v_mul_f32_e32 v37, v33, v33
	v_fmac_f32_e32 v36, v30, v30
	v_fmac_f32_e32 v37, v32, v32
	v_cvt_pk_bf16_f32 v30, v30, v31
	v_cvt_pk_bf16_f32 v31, v32, v33
	v_lshl_add_u64 v[32:33], v[34:35], 1, s[42:43]
	v_lshl_add_u64 v[32:33], v[136:137], 1, v[32:33]
	v_lshl_add_u64 v[32:33], v[32:33], 0, v[200:201]
	v_mov_b32_e32 v192, v30
	v_mov_b32_e32 v193, v31
	s_waitcnt vmcnt(10)
	v_lshlrev_b32_e32 v30, 16, v82
	v_and_b32_e32 v31, 0xffff0000, v82
	v_lshlrev_b32_e32 v34, 16, v83
	v_and_b32_e32 v35, 0xffff0000, v83
	v_pk_add_f32 v[28:29], v[28:29], v[34:35]
	v_pk_add_f32 v[26:27], v[26:27], v[30:31]
	v_mul_f32_e32 v31, v29, v29
	v_mul_f32_e32 v30, v27, v27
	v_fmac_f32_e32 v30, v26, v26
	v_fmac_f32_e32 v31, v28, v28
	v_add_f32_e32 v36, v36, v37
	v_add_f32_e32 v30, v30, v31
	v_add_f32_e32 v36, v36, v30
	s_waitcnt vmcnt(9)
	v_lshlrev_b32_e32 v30, 16, v78
	v_and_b32_e32 v31, 0xffff0000, v78
	v_lshlrev_b32_e32 v34, 16, v79
	v_and_b32_e32 v35, 0xffff0000, v79
	v_pk_add_f32 v[24:25], v[24:25], v[34:35]
	v_pk_add_f32 v[22:23], v[22:23], v[30:31]
	v_cvt_pk_bf16_f32 v26, v26, v27
	v_mul_f32_e32 v30, v25, v25
	v_mul_f32_e32 v27, v23, v23
	v_fmac_f32_e32 v27, v22, v22
	v_fmac_f32_e32 v30, v24, v24
	v_add_f32_e32 v27, v27, v30
	s_waitcnt vmcnt(8)
	v_lshlrev_b32_e32 v30, 16, v74
	v_and_b32_e32 v31, 0xffff0000, v74
	v_lshlrev_b32_e32 v34, 16, v75
	v_and_b32_e32 v35, 0xffff0000, v75
	v_pk_add_f32 v[20:21], v[20:21], v[34:35]
	v_pk_add_f32 v[30:31], v[18:19], v[30:31]
	v_mul_f32_e32 v19, v21, v21
	v_mul_f32_e32 v18, v31, v31
	v_fmac_f32_e32 v18, v30, v30
	v_fmac_f32_e32 v19, v20, v20
	v_add_f32_e32 v27, v36, v27
	v_add_f32_e32 v18, v18, v19
	v_add_f32_e32 v18, v27, v18
	v_mov_b32_e32 v19, v18
	s_nop 1
	v_permlane16_swap_b32_e32 v19, v18
	v_cvt_pk_bf16_f32 v27, v28, v29
	v_mov_b32_e32 v194, v26
	v_mov_b32_e32 v195, v27
	s_nop 1
	v_permlane16_swap_b32_e32 v192, v194
	v_permlane16_swap_b32_e32 v193, v195
	global_store_dwordx4 v[32:33], v[192:195], off
	v_cvt_pk_bf16_f32 v22, v22, v23
	v_cvt_pk_bf16_f32 v23, v24, v25
	s_waitcnt lgkmcnt(0)
	v_add_f32_e32 v18, v18, v19
	ds_bpermute_b32 v19, v115, v18
	v_mov_b32_e32 v196, v22
	v_mov_b32_e32 v197, v23
	v_cvt_pk_bf16_f32 v22, v30, v31
	v_cvt_pk_bf16_f32 v23, v20, v21
	v_mov_b32_e32 v198, v22
	v_mov_b32_e32 v199, v23
	s_nop 1
	v_permlane16_swap_b32_e32 v196, v198
	v_permlane16_swap_b32_e32 v197, v199
	global_store_dwordx4 v[32:33], v[196:199], off offset:256
	s_and_saveexec_b64 s[80:81], s[6:7]
	s_cbranch_execz .LBB0_1053
	v_readlane_b32 s12, v253, 40
	v_lshlrev_b64 v[20:21], 6, v[70:71]
	v_readlane_b32 s13, v253, 41
	s_lshl_b32 s64, s90, 2
	s_waitcnt lgkmcnt(0)
	v_add_f32_e32 v18, v18, v19
	v_lshl_add_u64 v[20:21], s[12:13], 0, v[20:21]
	v_lshl_add_u64 v[20:21], s[78:79], 2, v[20:21]
	v_lshl_add_u64 v[20:21], v[20:21], 0, s[64:65]
	global_store_dword v[20:21], v18, off
.LBB0_1053:
	s_or_b64 exec, exec, s[80:81]
	s_waitcnt vmcnt(9)
	v_lshlrev_b32_e32 v20, 16, v80
	v_and_b32_e32 v21, 0xffff0000, v80
	v_lshlrev_b32_e32 v22, 16, v81
	v_and_b32_e32 v23, 0xffff0000, v81
	v_pk_add_f32 v[16:17], v[16:17], v[22:23]
	v_pk_add_f32 v[14:15], v[14:15], v[20:21]
	s_waitcnt lgkmcnt(0)
	v_lshlrev_b64 v[18:19], 10, v[66:67]
	v_mul_f32_e32 v20, v15, v15
	v_mul_f32_e32 v21, v17, v17
	v_fmac_f32_e32 v20, v14, v14
	v_fmac_f32_e32 v21, v16, v16
	v_cvt_pk_bf16_f32 v14, v14, v15
	v_cvt_pk_bf16_f32 v15, v16, v17
	v_lshl_add_u64 v[16:17], v[18:19], 1, s[42:43]
	v_lshl_add_u64 v[16:17], v[136:137], 1, v[16:17]
	v_lshl_add_u64 v[16:17], v[16:17], 0, v[200:201]
	v_mov_b32_e32 v192, v14
	v_mov_b32_e32 v193, v15
	s_waitcnt vmcnt(9)
	v_lshlrev_b32_e32 v14, 16, v76
	v_and_b32_e32 v15, 0xffff0000, v76
	v_lshlrev_b32_e32 v18, 16, v77
	v_and_b32_e32 v19, 0xffff0000, v77
	v_pk_add_f32 v[12:13], v[12:13], v[18:19]
	v_pk_add_f32 v[10:11], v[10:11], v[14:15]
	v_mul_f32_e32 v15, v13, v13
	v_mul_f32_e32 v14, v11, v11
	v_fmac_f32_e32 v14, v10, v10
	v_fmac_f32_e32 v15, v12, v12
	v_add_f32_e32 v20, v20, v21
	v_add_f32_e32 v14, v14, v15
	v_add_f32_e32 v20, v20, v14
	s_waitcnt vmcnt(8)
	v_lshlrev_b32_e32 v14, 16, v72
	v_and_b32_e32 v15, 0xffff0000, v72
	v_lshlrev_b32_e32 v18, 16, v73
	v_and_b32_e32 v19, 0xffff0000, v73
	v_pk_add_f32 v[8:9], v[8:9], v[18:19]
	v_pk_add_f32 v[6:7], v[6:7], v[14:15]
	v_cvt_pk_bf16_f32 v10, v10, v11
	v_mul_f32_e32 v14, v9, v9
	v_mul_f32_e32 v11, v7, v7
	v_fmac_f32_e32 v11, v6, v6
	v_fmac_f32_e32 v14, v8, v8
	v_add_f32_e32 v11, v11, v14
	s_waitcnt vmcnt(8)
	v_lshlrev_b32_e32 v14, 16, v68
	v_and_b32_e32 v15, 0xffff0000, v68
	v_lshlrev_b32_e32 v18, 16, v69
	v_and_b32_e32 v19, 0xffff0000, v69
	v_pk_add_f32 v[4:5], v[4:5], v[18:19]
	v_pk_add_f32 v[14:15], v[2:3], v[14:15]
	v_mul_f32_e32 v3, v5, v5
	v_mul_f32_e32 v2, v15, v15
	v_fmac_f32_e32 v2, v14, v14
	v_fmac_f32_e32 v3, v4, v4
	v_add_f32_e32 v11, v20, v11
	v_add_f32_e32 v2, v2, v3
	v_add_f32_e32 v2, v11, v2
	v_mov_b32_e32 v3, v2
	s_nop 1
	v_permlane16_swap_b32_e32 v3, v2
	v_cvt_pk_bf16_f32 v11, v12, v13
	v_mov_b32_e32 v194, v10
	v_mov_b32_e32 v195, v11
	s_nop 1
	v_permlane16_swap_b32_e32 v192, v194
	v_permlane16_swap_b32_e32 v193, v195
	global_store_dwordx4 v[16:17], v[192:195], off
	v_cvt_pk_bf16_f32 v6, v6, v7
	v_cvt_pk_bf16_f32 v7, v8, v9
	s_waitcnt lgkmcnt(0)
	v_add_f32_e32 v2, v2, v3
	ds_bpermute_b32 v3, v115, v2
	v_mov_b32_e32 v196, v6
	v_mov_b32_e32 v197, v7
	v_cvt_pk_bf16_f32 v6, v14, v15
	v_cvt_pk_bf16_f32 v7, v4, v5
	v_mov_b32_e32 v198, v6
	v_mov_b32_e32 v199, v7
	s_nop 1
	v_permlane16_swap_b32_e32 v196, v198
	v_permlane16_swap_b32_e32 v197, v199
	global_store_dwordx4 v[16:17], v[196:199], off offset:256
	s_and_saveexec_b64 s[80:81], s[6:7]
	s_cbranch_execz .LBB0_1055
	v_readlane_b32 s12, v253, 40
	v_lshlrev_b64 v[4:5], 6, v[66:67]
	v_readlane_b32 s13, v253, 41
	s_lshl_b32 s64, s90, 2
	s_waitcnt lgkmcnt(0)
	v_add_f32_e32 v2, v2, v3
	v_lshl_add_u64 v[4:5], s[12:13], 0, v[4:5]
	v_lshl_add_u64 v[4:5], s[78:79], 2, v[4:5]
	v_lshl_add_u64 v[4:5], v[4:5], 0, s[64:65]
	global_store_dword v[4:5], v2, off

; __device__ __forceinline__ unsigned cvt_pk_bf16(float lo, float hi) { unsigned r; asm volatile("v_cvt_pk_bf16_f32 %0, %1, %2" : "=v"(r) : "v"(lo), "v"(hi)); return r; }
;     __device__ __forceinline__ void operator()(f32x4 (&acc)[2][2][4][2], const Unit& u, int wr, int wc, int fr, int fq) const {
;         const int col0 = u.pn * BM + wc * 32 + 4 * fq;
; #pragma unroll
;         for (int ai = 0; ai < 2; ++ai) {
;             unsigned long long old[4][2][2];
; #pragma unroll
;             for (int m = 0; m < 4; ++m) { const size_t off = (size_t)(u.pm * BM + ai * HALF + wr * 64 + m * 16 + fr) * ldc + col0;
; #pragma unroll
;                 for (int bj = 0; bj < 2; ++bj)
; #pragma unroll
;                     for (int n = 0; n < 2; ++n) old[m][bj][n] = *(const unsigned long long*)(xb + off + bj * HALF + n * 16); }
; #pragma unroll
;             for (int m = 0; m < 4; ++m) { const int row = u.pm * BM + ai * HALF + wr * 64 + m * 16 + fr; const size_t off = (size_t)row * ldc + col0; float sq = 0.f;
; #pragma unroll
;                 for (int bj = 0; bj < 2; ++bj)
; #pragma unroll
;                     for (int n = 0; n < 2; ++n) { const unsigned long long b = old[m][bj][n];
;                         const unsigned blo = (unsigned)b, bhi = (unsigned)(b >> 32);
;                         f32x4 v; v[0] = __builtin_bit_cast(float, blo << 16); v[1] = __builtin_bit_cast(float, blo & 0xffff0000u); v[2] = __builtin_bit_cast(float, bhi << 16); v[3] = __builtin_bit_cast(float, bhi & 0xffff0000u);
;                         v = v + acc[ai][bj][m][n];
;                         sq += (v[0] * v[0] + v[1] * v[1]) + (v[2] * v[2] + v[3] * v[3]);
;                         *(unsigned long long*)(xb + off + bj * HALF + n * 16) = (unsigned long long)cvt_pk_bf16(v[0], v[1]) | ((unsigned long long)cvt_pk_bf16(v[2], v[3]) << 32); }
;                 sq += __shfl_xor(sq, 16); sq += __shfl_xor(sq, 32);
;                 if (fq == 0) ssp[(size_t)row * 16 + 4 * u.pn + wc] = sq; }
.LBB0_1266:
	v_bfe_u32 v200, v229, 4, 1
	v_mul_u32_u24_e32 v200, 24, v200
	v_mov_b32_e32 v201, 0
	v_lshl_or_b32 v136, s12, 8, v174
	v_lshl_add_u32 v140, s13, 8, v172
	v_ashrrev_i32_e32 v137, 31, v136
	v_lshlrev_b64 v[176:177], 1, v[136:137]
	v_ashrrev_i32_e32 v141, 31, v140
	v_lshl_add_u64 v[138:139], s[42:43], 0, v[176:177]
	v_lshlrev_b64 v[178:179], 11, v[140:141]
	v_lshl_add_u64 v[142:143], v[138:139], 0, v[178:179]
	global_load_dwordx2 v[180:181], v[142:143], off
	global_load_dwordx2 v[182:183], v[142:143], off offset:32
	global_load_dwordx2 v[184:185], v[142:143], off offset:256
	global_load_dwordx2 v[188:189], v[142:143], off offset:288
	v_or_b32_e32 v160, 16, v140
	v_ashrrev_i32_e32 v161, 31, v160
	v_lshlrev_b64 v[142:143], 11, v[160:161]
	v_or_b32_e32 v146, 32, v140
	v_lshl_add_u64 v[142:143], v[138:139], 0, v[142:143]
	v_ashrrev_i32_e32 v147, 31, v146
	global_load_dwordx2 v[170:171], v[142:143], off
	global_load_dwordx2 v[168:169], v[142:143], off offset:32
	global_load_dwordx2 v[166:167], v[142:143], off offset:256
	global_load_dwordx2 v[164:165], v[142:143], off offset:288
	v_lshlrev_b64 v[142:143], 11, v[146:147]
	v_lshl_add_u64 v[142:143], v[138:139], 0, v[142:143]
	global_load_dwordx2 v[162:163], v[142:143], off
	global_load_dwordx2 v[158:159], v[142:143], off offset:32
	global_load_dwordx2 v[154:155], v[142:143], off offset:256
	global_load_dwordx2 v[150:151], v[142:143], off offset:288
	v_or_b32_e32 v142, 48, v140
	v_ashrrev_i32_e32 v143, 31, v142
	v_lshlrev_b64 v[144:145], 11, v[142:143]
	v_lshl_add_u64 v[144:145], v[138:139], 0, v[144:145]
	global_load_dwordx2 v[156:157], v[144:145], off
	global_load_dwordx2 v[152:153], v[144:145], off offset:32
	global_load_dwordx2 v[148:149], v[144:145], off offset:256
	s_nop 0
	global_load_dwordx2 v[144:145], v[144:145], off offset:288
	s_lshl_b32 s76, s12, 2
	s_ashr_i32 s77, s76, 31
	s_waitcnt vmcnt(0)
	s_mov_b32 s100, 1
	v_lshlrev_b32_e32 v190, 16, v180
	v_and_b32_e32 v191, 0xffff0000, v180
	v_lshlrev_b32_e32 v180, 16, v181
	v_and_b32_e32 v181, 0xffff0000, v181
	v_pk_add_f32 v[128:129], v[128:129], v[180:181]
	v_pk_add_f32 v[126:127], v[126:127], v[190:191]
	v_mul_f32_e32 v181, v129, v129
	v_mul_f32_e32 v180, v127, v127
	v_fmac_f32_e32 v180, v126, v126
	v_fmac_f32_e32 v181, v128, v128
	v_cvt_pk_bf16_f32 v126, v126, v127
	v_cvt_pk_bf16_f32 v127, v128, v129
	v_lshl_add_u64 v[128:129], s[42:43], 0, v[178:179]
	v_lshl_add_u64 v[128:129], v[128:129], 0, v[176:177]
	v_lshl_add_u64 v[128:129], v[128:129], 0, v[200:201]
	v_mov_b32_e32 v192, v126
	v_mov_b32_e32 v193, v127
	v_lshlrev_b32_e32 v126, 16, v182
	v_and_b32_e32 v127, 0xffff0000, v182
	v_pk_add_f32 v[122:123], v[122:123], v[126:127]
	v_lshlrev_b32_e32 v176, 16, v183
	v_and_b32_e32 v177, 0xffff0000, v183
	v_mul_f32_e32 v126, v123, v123
	v_pk_add_f32 v[124:125], v[124:125], v[176:177]
	v_fmac_f32_e32 v126, v122, v122
	v_cvt_pk_bf16_f32 v122, v122, v123
	v_cvt_pk_bf16_f32 v123, v124, v125
	v_mul_f32_e32 v127, v125, v125
	v_mov_b32_e32 v194, v122
	v_mov_b32_e32 v195, v123
	s_nop 1
	v_permlane16_swap_b32_e32 v192, v194
	v_permlane16_swap_b32_e32 v193, v195
	global_store_dwordx4 v[128:129], v[192:195], off
	v_lshlrev_b32_e32 v122, 16, v184
	v_and_b32_e32 v123, 0xffff0000, v184
	v_fmac_f32_e32 v127, v124, v124
	v_lshlrev_b32_e32 v124, 16, v185
	v_and_b32_e32 v125, 0xffff0000, v185
	v_pk_add_f32 v[118:119], v[118:119], v[122:123]
	v_pk_add_f32 v[120:121], v[120:121], v[124:125]
	v_mul_f32_e32 v122, v119, v119
	v_fmac_f32_e32 v122, v118, v118
	v_mul_f32_e32 v123, v121, v121
	v_cvt_pk_bf16_f32 v118, v118, v119
	v_cvt_pk_bf16_f32 v119, v120, v121
	v_fmac_f32_e32 v123, v120, v120
	v_mov_b32_e32 v196, v118
	v_mov_b32_e32 v197, v119
	v_lshlrev_b32_e32 v118, 16, v188
	v_and_b32_e32 v119, 0xffff0000, v188
	v_lshlrev_b32_e32 v120, 16, v189
	v_and_b32_e32 v121, 0xffff0000, v189
	v_pk_add_f32 v[116:117], v[116:117], v[120:121]
	v_pk_add_f32 v[118:119], v[114:115], v[118:119]
	v_add_f32_e32 v180, v180, v181
	v_add_f32_e32 v126, v126, v127
	v_mul_f32_e32 v114, v119, v119
	v_mul_f32_e32 v115, v117, v117
	v_add_f32_e32 v126, v180, v126
	v_add_f32_e32 v122, v122, v123
	v_fmac_f32_e32 v114, v118, v118
	v_fmac_f32_e32 v115, v116, v116
	v_add_f32_e32 v122, v126, v122
	v_add_f32_e32 v114, v114, v115
	v_cvt_pk_bf16_f32 v118, v118, v119
	v_cvt_pk_bf16_f32 v119, v116, v117
	v_and_b32_e32 v116, 64, v229
	v_add_f32_e32 v115, v122, v114
	v_xor_b32_e32 v114, 16, v229
	v_add_u32_e32 v117, 64, v116
	v_cmp_lt_i32_e32 vcc, v114, v117
	v_mov_b32_e32 v198, v118
	v_mov_b32_e32 v199, v119
	s_nop 1
	v_permlane16_swap_b32_e32 v196, v198
	v_permlane16_swap_b32_e32 v197, v199
	global_store_dwordx4 v[128:129], v[196:199], off offset:256
	s_nop 0
	v_cndmask_b32_e32 v114, v229, v114, vcc
	v_lshlrev_b32_e32 v114, 2, v114
	v_mov_b32_e32 v116, v115
	s_nop 1
	v_permlane16_swap_b32_e32 v116, v115
	s_waitcnt lgkmcnt(0)
	v_add_f32_e32 v116, v115, v116
	v_xor_b32_e32 v115, 32, v229
	v_cmp_lt_i32_e32 vcc, v115, v117
	s_nop 1
	v_cndmask_b32_e32 v115, v229, v115, vcc
	v_lshlrev_b32_e32 v115, 2, v115
	ds_bpermute_b32 v117, v115, v116
	s_and_saveexec_b64 s[78:79], s[6:7]
	s_cbranch_execz .LBB0_1268
	v_lshlrev_b64 v[118:119], 6, v[140:141]
	v_lshl_add_u64 v[118:119], s[14:15], 0, v[118:119]
	v_lshl_add_u64 v[118:119], s[76:77], 2, v[118:119]
	s_lshl_b32 s64, s86, 2
	v_lshl_add_u64 v[118:119], v[118:119], 0, s[64:65]
	s_waitcnt lgkmcnt(0)
	v_add_f32_e32 v116, v116, v117
	global_store_dword v[118:119], v116, off
; __device__ __forceinline__ unsigned cvt_pk_bf16(float lo, float hi) { unsigned r; asm volatile("v_cvt_pk_bf16_f32 %0, %1, %2" : "=v"(r) : "v"(lo), "v"(hi)); return r; }
;     __device__ __forceinline__ void operator()(f32x4 (&acc)[2][2][4][2], const Unit& u, int wr, int wc, int fr, int fq) const {
;     ...
;             for (int m = 0; m < 4; ++m) { const int row = u.pm * BM + ai * HALF + wr * 64 + m * 16 + fr; const size_t off = (size_t)row * ldc + col0; float sq = 0.f;
; #pragma unroll
;                 for (int bj = 0; bj < 2; ++bj)
; #pragma unroll
;                     for (int n = 0; n < 2; ++n) { const unsigned long long b = old[m][bj][n];
;                         const unsigned blo = (unsigned)b, bhi = (unsigned)(b >> 32);
;                         f32x4 v; v[0] = __builtin_bit_cast(float, blo << 16); v[1] = __builtin_bit_cast(float, blo & 0xffff0000u); v[2] = __builtin_bit_cast(float, bhi << 16); v[3] = __builtin_bit_cast(float, bhi & 0xffff0000u);
;                         v = v + acc[ai][bj][m][n];
;                         sq += (v[0] * v[0] + v[1] * v[1]) + (v[2] * v[2] + v[3] * v[3]);
;                         *(unsigned long long*)(xb + off + bj * HALF + n * 16) = (unsigned long long)cvt_pk_bf16(v[0], v[1]) | ((unsigned long long)cvt_pk_bf16(v[2], v[3]) << 32); }
;                 sq += __shfl_xor(sq, 16); sq += __shfl_xor(sq, 32);
;                 if (fq == 0) ssp[(size_t)row * 16 + 4 * u.pn + wc] = sq; }
.LBB0_1268:
	s_or_b64 exec, exec, s[78:79]
	v_lshlrev_b32_e32 v118, 16, v170
	v_and_b32_e32 v119, 0xffff0000, v170
	v_lshlrev_b32_e32 v120, 16, v171
	v_and_b32_e32 v121, 0xffff0000, v171
	v_pk_add_f32 v[112:113], v[112:113], v[120:121]
	v_pk_add_f32 v[110:111], v[110:111], v[118:119]
	s_waitcnt lgkmcnt(0)
	v_lshlrev_b64 v[116:117], 10, v[160:161]
	v_mul_f32_e32 v118, v111, v111
	v_mul_f32_e32 v119, v113, v113
	v_fmac_f32_e32 v118, v110, v110
	v_fmac_f32_e32 v119, v112, v112
	v_cvt_pk_bf16_f32 v110, v110, v111
	v_cvt_pk_bf16_f32 v111, v112, v113
	v_lshl_add_u64 v[112:113], v[116:117], 1, s[42:43]
	v_lshl_add_u64 v[112:113], v[136:137], 1, v[112:113]
	v_lshl_add_u64 v[112:113], v[112:113], 0, v[200:201]
	v_mov_b32_e32 v192, v110
	v_mov_b32_e32 v193, v111
	v_lshlrev_b32_e32 v110, 16, v168
	v_and_b32_e32 v111, 0xffff0000, v168
	v_lshlrev_b32_e32 v116, 16, v169
	v_and_b32_e32 v117, 0xffff0000, v169
	v_pk_add_f32 v[108:109], v[108:109], v[116:117]
	v_pk_add_f32 v[106:107], v[106:107], v[110:111]
	v_mul_f32_e32 v111, v109, v109
	v_mul_f32_e32 v110, v107, v107
	v_fmac_f32_e32 v110, v106, v106
	v_fmac_f32_e32 v111, v108, v108
	v_add_f32_e32 v118, v118, v119
	v_add_f32_e32 v110, v110, v111
	v_add_f32_e32 v118, v118, v110
	v_lshlrev_b32_e32 v110, 16, v166
	v_and_b32_e32 v111, 0xffff0000, v166
	v_lshlrev_b32_e32 v116, 16, v167
	v_and_b32_e32 v117, 0xffff0000, v167
	v_pk_add_f32 v[104:105], v[104:105], v[116:117]
	v_pk_add_f32 v[102:103], v[102:103], v[110:111]
	v_cvt_pk_bf16_f32 v106, v106, v107
	v_mul_f32_e32 v110, v105, v105
	v_mul_f32_e32 v107, v103, v103
	v_fmac_f32_e32 v107, v102, v102
	v_fmac_f32_e32 v110, v104, v104
	v_add_f32_e32 v107, v107, v110
	v_lshlrev_b32_e32 v110, 16, v164
	v_and_b32_e32 v111, 0xffff0000, v164
	v_lshlrev_b32_e32 v116, 16, v165
	v_and_b32_e32 v117, 0xffff0000, v165
	v_pk_add_f32 v[100:101], v[100:101], v[116:117]
	v_pk_add_f32 v[110:111], v[98:99], v[110:111]
	v_mul_f32_e32 v99, v101, v101
	v_mul_f32_e32 v98, v111, v111
	v_fmac_f32_e32 v98, v110, v110
	v_fmac_f32_e32 v99, v100, v100
	v_add_f32_e32 v107, v118, v107
	v_add_f32_e32 v98, v98, v99
	v_add_f32_e32 v98, v107, v98
	v_mov_b32_e32 v99, v98
	s_nop 1
	v_permlane16_swap_b32_e32 v99, v98
	v_cvt_pk_bf16_f32 v107, v108, v109
	v_mov_b32_e32 v194, v106
	v_mov_b32_e32 v195, v107
	s_nop 1
	v_permlane16_swap_b32_e32 v192, v194
	v_permlane16_swap_b32_e32 v193, v195
	global_store_dwordx4 v[112:113], v[192:195], off
	v_cvt_pk_bf16_f32 v102, v102, v103
	v_cvt_pk_bf16_f32 v103, v104, v105
	s_waitcnt lgkmcnt(0)
	v_add_f32_e32 v98, v98, v99
	ds_bpermute_b32 v99, v115, v98
	v_mov_b32_e32 v196, v102
	v_mov_b32_e32 v197, v103
	v_cvt_pk_bf16_f32 v102, v110, v111
	v_cvt_pk_bf16_f32 v103, v100, v101
	v_mov_b32_e32 v198, v102
	v_mov_b32_e32 v199, v103
	s_nop 1
	v_permlane16_swap_b32_e32 v196, v198
	v_permlane16_swap_b32_e32 v197, v199
	global_store_dwordx4 v[112:113], v[196:199], off offset:256
	s_and_saveexec_b64 s[78:79], s[6:7]
	s_cbranch_execz .LBB0_1270
	v_lshlrev_b64 v[100:101], 6, v[160:161]
	v_lshl_add_u64 v[100:101], s[14:15], 0, v[100:101]
	v_lshl_add_u64 v[100:101], s[76:77], 2, v[100:101]
	s_lshl_b32 s64, s86, 2
	v_lshl_add_u64 v[100:101], v[100:101], 0, s[64:65]
	s_waitcnt lgkmcnt(0)
	v_add_f32_e32 v98, v98, v99
	global_store_dword v[100:101], v98, off
.LBB0_1270:
	s_or_b64 exec, exec, s[78:79]
	v_lshlrev_b32_e32 v100, 16, v162
	v_and_b32_e32 v101, 0xffff0000, v162
	v_lshlrev_b32_e32 v102, 16, v163
	v_and_b32_e32 v103, 0xffff0000, v163
	v_pk_add_f32 v[96:97], v[96:97], v[102:103]
	v_pk_add_f32 v[94:95], v[94:95], v[100:101]
	s_waitcnt lgkmcnt(0)
	v_lshlrev_b64 v[98:99], 10, v[146:147]
	v_mul_f32_e32 v100, v95, v95
	v_mul_f32_e32 v101, v97, v97
	v_fmac_f32_e32 v100, v94, v94
	v_fmac_f32_e32 v101, v96, v96
	v_cvt_pk_bf16_f32 v94, v94, v95
	v_cvt_pk_bf16_f32 v95, v96, v97
	v_lshl_add_u64 v[96:97], v[98:99], 1, s[42:43]
	v_lshl_add_u64 v[96:97], v[136:137], 1, v[96:97]
	v_lshl_add_u64 v[96:97], v[96:97], 0, v[200:201]
	v_mov_b32_e32 v192, v94
	v_mov_b32_e32 v193, v95
	v_lshlrev_b32_e32 v94, 16, v158
	v_and_b32_e32 v95, 0xffff0000, v158
	v_lshlrev_b32_e32 v98, 16, v159
	v_and_b32_e32 v99, 0xffff0000, v159
	v_pk_add_f32 v[92:93], v[92:93], v[98:99]
	v_pk_add_f32 v[90:91], v[90:91], v[94:95]
	v_mul_f32_e32 v95, v93, v93
	v_mul_f32_e32 v94, v91, v91
	v_fmac_f32_e32 v94, v90, v90
	v_fmac_f32_e32 v95, v92, v92
	v_add_f32_e32 v100, v100, v101
	v_add_f32_e32 v94, v94, v95
	v_add_f32_e32 v100, v100, v94
	v_lshlrev_b32_e32 v94, 16, v154
	v_and_b32_e32 v95, 0xffff0000, v154
	v_lshlrev_b32_e32 v98, 16, v155
	v_and_b32_e32 v99, 0xffff0000, v155
	v_pk_add_f32 v[88:89], v[88:89], v[98:99]
	v_pk_add_f32 v[86:87], v[86:87], v[94:95]
	v_cvt_pk_bf16_f32 v90, v90, v91
	v_mul_f32_e32 v94, v89, v89
	v_mul_f32_e32 v91, v87, v87
	v_fmac_f32_e32 v91, v86, v86
	v_fmac_f32_e32 v94, v88, v88
	v_add_f32_e32 v91, v91, v94
	v_lshlrev_b32_e32 v94, 16, v150
	v_and_b32_e32 v95, 0xffff0000, v150
	v_lshlrev_b32_e32 v98, 16, v151
	v_and_b32_e32 v99, 0xffff0000, v151
	v_pk_add_f32 v[84:85], v[84:85], v[98:99]
	v_pk_add_f32 v[94:95], v[82:83], v[94:95]
	v_mul_f32_e32 v83, v85, v85
	v_mul_f32_e32 v82, v95, v95
	v_fmac_f32_e32 v82, v94, v94
	v_fmac_f32_e32 v83, v84, v84
	v_add_f32_e32 v91, v100, v91
	v_add_f32_e32 v82, v82, v83
	v_add_f32_e32 v82, v91, v82
	v_mov_b32_e32 v83, v82
	s_nop 1
	v_permlane16_swap_b32_e32 v83, v82
	v_cvt_pk_bf16_f32 v91, v92, v93
	v_mov_b32_e32 v194, v90
	v_mov_b32_e32 v195, v91
	s_nop 1
	v_permlane16_swap_b32_e32 v192, v194
	v_permlane16_swap_b32_e32 v193, v195
	global_store_dwordx4 v[96:97], v[192:195], off
	v_cvt_pk_bf16_f32 v86, v86, v87
	v_cvt_pk_bf16_f32 v87, v88, v89
	s_waitcnt lgkmcnt(0)
	v_add_f32_e32 v82, v82, v83
	ds_bpermute_b32 v83, v115, v82
	v_mov_b32_e32 v196, v86
	v_mov_b32_e32 v197, v87
	v_cvt_pk_bf16_f32 v86, v94, v95
	v_cvt_pk_bf16_f32 v87, v84, v85
	v_mov_b32_e32 v198, v86
	v_mov_b32_e32 v199, v87
	s_nop 1
	v_permlane16_swap_b32_e32 v196, v198
	v_permlane16_swap_b32_e32 v197, v199
	global_store_dwordx4 v[96:97], v[196:199], off offset:256
	s_and_saveexec_b64 s[78:79], s[6:7]
	s_cbranch_execz .LBB0_1272
	v_lshlrev_b64 v[84:85], 6, v[146:147]
	v_lshl_add_u64 v[84:85], s[14:15], 0, v[84:85]
	v_lshl_add_u64 v[84:85], s[76:77], 2, v[84:85]
	s_lshl_b32 s64, s86, 2
	v_lshl_add_u64 v[84:85], v[84:85], 0, s[64:65]
	s_waitcnt lgkmcnt(0)
	v_add_f32_e32 v82, v82, v83
	global_store_dword v[84:85], v82, off
; __device__ __forceinline__ unsigned cvt_pk_bf16(float lo, float hi) { unsigned r; asm volatile("v_cvt_pk_bf16_f32 %0, %1, %2" : "=v"(r) : "v"(lo), "v"(hi)); return r; }
;     __device__ __forceinline__ void operator()(f32x4 (&acc)[2][2][4][2], const Unit& u, int wr, int wc, int fr, int fq) const {
;     ...
;             for (int m = 0; m < 4; ++m) { const size_t off = (size_t)(u.pm * BM + ai * HALF + wr * 64 + m * 16 + fr) * ldc + col0;
; #pragma unroll
;                 for (int bj = 0; bj < 2; ++bj)
; #pragma unroll
;                     for (int n = 0; n < 2; ++n) old[m][bj][n] = *(const unsigned long long*)(xb + off + bj * HALF + n * 16); }
; #pragma unroll
;             for (int m = 0; m < 4; ++m) { const int row = u.pm * BM + ai * HALF + wr * 64 + m * 16 + fr; const size_t off = (size_t)row * ldc + col0; float sq = 0.f;
; #pragma unroll
;                 for (int bj = 0; bj < 2; ++bj)
; #pragma unroll
;                     for (int n = 0; n < 2; ++n) { const unsigned long long b = old[m][bj][n];
;                         const unsigned blo = (unsigned)b, bhi = (unsigned)(b >> 32);
;                         f32x4 v; v[0] = __builtin_bit_cast(float, blo << 16); v[1] = __builtin_bit_cast(float, blo & 0xffff0000u); v[2] = __builtin_bit_cast(float, bhi << 16); v[3] = __builtin_bit_cast(float, bhi & 0xffff0000u);
;                         v = v + acc[ai][bj][m][n];
;                         sq += (v[0] * v[0] + v[1] * v[1]) + (v[2] * v[2] + v[3] * v[3]);
;                         *(unsigned long long*)(xb + off + bj * HALF + n * 16) = (unsigned long long)cvt_pk_bf16(v[0], v[1]) | ((unsigned long long)cvt_pk_bf16(v[2], v[3]) << 32); }
;                 sq += __shfl_xor(sq, 16); sq += __shfl_xor(sq, 32);
;                 if (fq == 0) ssp[(size_t)row * 16 + 4 * u.pn + wc] = sq; }
.LBB0_1272:
	s_or_b64 exec, exec, s[78:79]
	v_lshlrev_b32_e32 v84, 16, v156
	v_and_b32_e32 v85, 0xffff0000, v156
	v_lshlrev_b32_e32 v86, 16, v157
	v_and_b32_e32 v87, 0xffff0000, v157
	v_pk_add_f32 v[80:81], v[80:81], v[86:87]
	v_pk_add_f32 v[78:79], v[78:79], v[84:85]
	s_waitcnt lgkmcnt(0)
	v_lshlrev_b64 v[82:83], 10, v[142:143]
	v_mul_f32_e32 v84, v79, v79
	v_mul_f32_e32 v85, v81, v81
	v_fmac_f32_e32 v84, v78, v78
	v_fmac_f32_e32 v85, v80, v80
	v_cvt_pk_bf16_f32 v78, v78, v79
	v_cvt_pk_bf16_f32 v79, v80, v81
	v_lshl_add_u64 v[80:81], v[82:83], 1, s[42:43]
	v_lshl_add_u64 v[80:81], v[136:137], 1, v[80:81]
	v_lshl_add_u64 v[80:81], v[80:81], 0, v[200:201]
	v_mov_b32_e32 v192, v78
	v_mov_b32_e32 v193, v79
	v_lshlrev_b32_e32 v78, 16, v152
	v_and_b32_e32 v79, 0xffff0000, v152
	v_lshlrev_b32_e32 v82, 16, v153
	v_and_b32_e32 v83, 0xffff0000, v153
	v_pk_add_f32 v[76:77], v[76:77], v[82:83]
	v_pk_add_f32 v[74:75], v[74:75], v[78:79]
	v_mul_f32_e32 v79, v77, v77
	v_mul_f32_e32 v78, v75, v75
	v_fmac_f32_e32 v78, v74, v74
	v_fmac_f32_e32 v79, v76, v76
	v_add_f32_e32 v84, v84, v85
	v_add_f32_e32 v78, v78, v79
	v_add_f32_e32 v84, v84, v78
	v_lshlrev_b32_e32 v78, 16, v148
	v_and_b32_e32 v79, 0xffff0000, v148
	v_lshlrev_b32_e32 v82, 16, v149
	v_and_b32_e32 v83, 0xffff0000, v149
	v_pk_add_f32 v[72:73], v[72:73], v[82:83]
	v_pk_add_f32 v[70:71], v[70:71], v[78:79]
	v_cvt_pk_bf16_f32 v74, v74, v75
	v_mul_f32_e32 v78, v73, v73
	v_mul_f32_e32 v75, v71, v71
	v_fmac_f32_e32 v75, v70, v70
	v_fmac_f32_e32 v78, v72, v72
	v_add_f32_e32 v75, v75, v78
	v_lshlrev_b32_e32 v78, 16, v144
	v_and_b32_e32 v79, 0xffff0000, v144
	v_lshlrev_b32_e32 v82, 16, v145
	v_and_b32_e32 v83, 0xffff0000, v145
	v_pk_add_f32 v[68:69], v[68:69], v[82:83]
	v_pk_add_f32 v[78:79], v[66:67], v[78:79]
	v_mul_f32_e32 v67, v69, v69
	v_mul_f32_e32 v66, v79, v79
	v_fmac_f32_e32 v66, v78, v78
	v_fmac_f32_e32 v67, v68, v68
	v_add_f32_e32 v75, v84, v75
	v_add_f32_e32 v66, v66, v67
	v_add_f32_e32 v66, v75, v66
	v_mov_b32_e32 v67, v66
	s_nop 1
	v_permlane16_swap_b32_e32 v67, v66
	v_cvt_pk_bf16_f32 v75, v76, v77
	v_mov_b32_e32 v194, v74
	v_mov_b32_e32 v195, v75
	s_nop 1
	v_permlane16_swap_b32_e32 v192, v194
	v_permlane16_swap_b32_e32 v193, v195
	global_store_dwordx4 v[80:81], v[192:195], off
	v_cvt_pk_bf16_f32 v70, v70, v71
	v_cvt_pk_bf16_f32 v71, v72, v73
	s_waitcnt lgkmcnt(0)
	v_add_f32_e32 v66, v66, v67
	ds_bpermute_b32 v67, v115, v66
	v_mov_b32_e32 v196, v70
	v_mov_b32_e32 v197, v71
	v_cvt_pk_bf16_f32 v70, v78, v79
	v_cvt_pk_bf16_f32 v71, v68, v69
	v_mov_b32_e32 v198, v70
	v_mov_b32_e32 v199, v71
	s_nop 1
	v_permlane16_swap_b32_e32 v196, v198
	v_permlane16_swap_b32_e32 v197, v199
	global_store_dwordx4 v[80:81], v[196:199], off offset:256
	s_and_saveexec_b64 s[78:79], s[6:7]
	s_cbranch_execz .LBB0_1274
	v_lshlrev_b64 v[68:69], 6, v[142:143]
	v_lshl_add_u64 v[68:69], s[14:15], 0, v[68:69]
	v_lshl_add_u64 v[68:69], s[76:77], 2, v[68:69]
	s_lshl_b32 s64, s86, 2
	v_lshl_add_u64 v[68:69], v[68:69], 0, s[64:65]
	s_waitcnt lgkmcnt(0)
	v_add_f32_e32 v66, v66, v67
	global_store_dword v[68:69], v66, off
.LBB0_1274:
	s_or_b64 exec, exec, s[78:79]
	v_add_u32_e32 v96, 0x80, v140
	v_ashrrev_i32_e32 v97, 31, v96
	v_lshlrev_b64 v[102:103], 11, v[96:97]
	s_waitcnt lgkmcnt(0)
	v_lshl_add_u64 v[66:67], v[138:139], 0, v[102:103]
	global_load_dwordx2 v[104:105], v[66:67], off
	global_load_dwordx2 v[106:107], v[66:67], off offset:32
	global_load_dwordx2 v[100:101], v[66:67], off offset:256
	global_load_dwordx2 v[98:99], v[66:67], off offset:288
	v_add_u32_e32 v84, 0x90, v140
	v_ashrrev_i32_e32 v85, 31, v84
	v_lshlrev_b64 v[66:67], 11, v[84:85]
	v_add_u32_e32 v70, 0xa0, v140
	v_lshl_add_u64 v[66:67], v[138:139], 0, v[66:67]
	v_ashrrev_i32_e32 v71, 31, v70
	global_load_dwordx2 v[94:95], v[66:67], off
	global_load_dwordx2 v[92:93], v[66:67], off offset:32
	global_load_dwordx2 v[90:91], v[66:67], off offset:256
	global_load_dwordx2 v[88:89], v[66:67], off offset:288
	v_lshlrev_b64 v[66:67], 11, v[70:71]
	v_lshl_add_u64 v[66:67], v[138:139], 0, v[66:67]
	global_load_dwordx2 v[86:87], v[66:67], off
	global_load_dwordx2 v[82:83], v[66:67], off offset:32
	global_load_dwordx2 v[78:79], v[66:67], off offset:256
	global_load_dwordx2 v[74:75], v[66:67], off offset:288
	v_add_u32_e32 v66, 0xb0, v140
	v_ashrrev_i32_e32 v67, 31, v66
	v_lshlrev_b64 v[68:69], 11, v[66:67]
	v_lshl_add_u64 v[68:69], v[138:139], 0, v[68:69]
	global_load_dwordx2 v[80:81], v[68:69], off
	global_load_dwordx2 v[76:77], v[68:69], off offset:32
	global_load_dwordx2 v[72:73], v[68:69], off offset:256
	s_nop 0
	global_load_dwordx2 v[68:69], v[68:69], off offset:288
	s_waitcnt vmcnt(15)
	v_lshlrev_b32_e32 v108, 16, v104
	v_and_b32_e32 v109, 0xffff0000, v104
	v_lshlrev_b32_e32 v104, 16, v105
	v_and_b32_e32 v105, 0xffff0000, v105
	v_pk_add_f32 v[64:65], v[64:65], v[104:105]
	v_pk_add_f32 v[62:63], v[62:63], v[108:109]
	v_mul_f32_e32 v105, v65, v65
	v_mul_f32_e32 v104, v63, v63
	v_fmac_f32_e32 v104, v62, v62
	v_fmac_f32_e32 v105, v64, v64
	v_add_f32_e32 v108, v104, v105
	v_cvt_pk_bf16_f32 v104, v62, v63
	v_cvt_pk_bf16_f32 v105, v64, v65
	s_waitcnt vmcnt(14)
	v_lshlrev_b32_e32 v64, 16, v106
	v_and_b32_e32 v65, 0xffff0000, v106
	v_lshl_add_u64 v[62:63], s[42:43], 0, v[102:103]
	v_pk_add_f32 v[58:59], v[58:59], v[64:65]
	v_lshl_add_u64 v[62:63], v[136:137], 1, v[62:63]
	v_lshlrev_b32_e32 v102, 16, v107
	v_and_b32_e32 v103, 0xffff0000, v107
	v_mul_f32_e32 v64, v59, v59
	v_lshl_add_u64 v[62:63], v[62:63], 0, v[200:201]
	v_mov_b32_e32 v192, v104
	v_mov_b32_e32 v193, v105
	v_pk_add_f32 v[60:61], v[60:61], v[102:103]
	v_fmac_f32_e32 v64, v58, v58
	v_cvt_pk_bf16_f32 v58, v58, v59
	v_cvt_pk_bf16_f32 v59, v60, v61
	v_mul_f32_e32 v65, v61, v61
	v_mov_b32_e32 v194, v58
	v_mov_b32_e32 v195, v59
	s_nop 1
	v_permlane16_swap_b32_e32 v192, v194
	v_permlane16_swap_b32_e32 v193, v195
	global_store_dwordx4 v[62:63], v[192:195], off
	s_waitcnt vmcnt(14)
; __device__ __forceinline__ unsigned cvt_pk_bf16(float lo, float hi) { unsigned r; asm volatile("v_cvt_pk_bf16_f32 %0, %1, %2" : "=v"(r) : "v"(lo), "v"(hi)); return r; }
;     __device__ __forceinline__ void operator()(f32x4 (&acc)[2][2][4][2], const Unit& u, int wr, int wc, int fr, int fq) const {
;     ...
;             for (int m = 0; m < 4; ++m) { const int row = u.pm * BM + ai * HALF + wr * 64 + m * 16 + fr; const size_t off = (size_t)row * ldc + col0; float sq = 0.f;
; #pragma unroll
;                 for (int bj = 0; bj < 2; ++bj)
; #pragma unroll
;                     for (int n = 0; n < 2; ++n) { const unsigned long long b = old[m][bj][n];
;                         const unsigned blo = (unsigned)b, bhi = (unsigned)(b >> 32);
;                         f32x4 v; v[0] = __builtin_bit_cast(float, blo << 16); v[1] = __builtin_bit_cast(float, blo & 0xffff0000u); v[2] = __builtin_bit_cast(float, bhi << 16); v[3] = __builtin_bit_cast(float, bhi & 0xffff0000u);
;                         v = v + acc[ai][bj][m][n];
;                         sq += (v[0] * v[0] + v[1] * v[1]) + (v[2] * v[2] + v[3] * v[3]);
;                         *(unsigned long long*)(xb + off + bj * HALF + n * 16) = (unsigned long long)cvt_pk_bf16(v[0], v[1]) | ((unsigned long long)cvt_pk_bf16(v[2], v[3]) << 32); }
;                 sq += __shfl_xor(sq, 16); sq += __shfl_xor(sq, 32);
;                 if (fq == 0) ssp[(size_t)row * 16 + 4 * u.pn + wc] = sq; }
	v_lshlrev_b32_e32 v58, 16, v100
	v_and_b32_e32 v59, 0xffff0000, v100
	v_fmac_f32_e32 v65, v60, v60
	v_lshlrev_b32_e32 v60, 16, v101
	v_and_b32_e32 v61, 0xffff0000, v101
	v_pk_add_f32 v[54:55], v[54:55], v[58:59]
	v_pk_add_f32 v[56:57], v[56:57], v[60:61]
	v_mul_f32_e32 v58, v55, v55
	v_fmac_f32_e32 v58, v54, v54
	v_mul_f32_e32 v59, v57, v57
	v_cvt_pk_bf16_f32 v54, v54, v55
	v_cvt_pk_bf16_f32 v55, v56, v57
	v_fmac_f32_e32 v59, v56, v56
	v_mov_b32_e32 v196, v54
	v_mov_b32_e32 v197, v55
	s_waitcnt vmcnt(13)
	v_lshlrev_b32_e32 v54, 16, v98
	v_and_b32_e32 v55, 0xffff0000, v98
	v_lshlrev_b32_e32 v56, 16, v99
	v_and_b32_e32 v57, 0xffff0000, v99
	v_pk_add_f32 v[52:53], v[52:53], v[56:57]
	v_pk_add_f32 v[50:51], v[50:51], v[54:55]
	v_add_f32_e32 v64, v64, v65
	v_mul_f32_e32 v54, v51, v51
	v_mul_f32_e32 v55, v53, v53
	v_add_f32_e32 v64, v108, v64
	v_add_f32_e32 v58, v58, v59
	v_fmac_f32_e32 v54, v50, v50
	v_fmac_f32_e32 v55, v52, v52
	v_add_f32_e32 v58, v64, v58
	v_add_f32_e32 v54, v54, v55
	v_add_f32_e32 v54, v58, v54
	v_cvt_pk_bf16_f32 v50, v50, v51
	v_cvt_pk_bf16_f32 v51, v52, v53
	v_mov_b32_e32 v198, v50
	v_mov_b32_e32 v199, v51
	s_nop 1
	v_permlane16_swap_b32_e32 v196, v198
	v_permlane16_swap_b32_e32 v197, v199
	global_store_dwordx4 v[62:63], v[196:199], off offset:256
	ds_bpermute_b32 v50, v114, v54
	s_waitcnt lgkmcnt(0)
	v_add_f32_e32 v50, v54, v50
	ds_bpermute_b32 v51, v115, v50
	s_and_saveexec_b64 s[78:79], s[6:7]
	s_cbranch_execz .LBB0_1276
	v_lshlrev_b64 v[52:53], 6, v[96:97]
	v_lshl_add_u64 v[52:53], s[14:15], 0, v[52:53]
	v_lshl_add_u64 v[52:53], s[76:77], 2, v[52:53]
	s_lshl_b32 s64, s86, 2
	v_lshl_add_u64 v[52:53], v[52:53], 0, s[64:65]
	s_waitcnt lgkmcnt(0)
	v_add_f32_e32 v50, v50, v51
	global_store_dword v[52:53], v50, off
.LBB0_1276:
	s_or_b64 exec, exec, s[78:79]
	s_waitcnt vmcnt(13)
	v_lshlrev_b32_e32 v52, 16, v94
	v_and_b32_e32 v53, 0xffff0000, v94
	v_lshlrev_b32_e32 v54, 16, v95
	v_and_b32_e32 v55, 0xffff0000, v95
	v_pk_add_f32 v[48:49], v[48:49], v[54:55]
	v_pk_add_f32 v[46:47], v[46:47], v[52:53]
	s_waitcnt lgkmcnt(0)
	v_lshlrev_b64 v[50:51], 10, v[84:85]
	v_mul_f32_e32 v52, v47, v47
	v_mul_f32_e32 v53, v49, v49
	v_fmac_f32_e32 v52, v46, v46
	v_fmac_f32_e32 v53, v48, v48
	v_cvt_pk_bf16_f32 v46, v46, v47
	v_cvt_pk_bf16_f32 v47, v48, v49
	v_lshl_add_u64 v[48:49], v[50:51], 1, s[42:43]
	v_lshl_add_u64 v[48:49], v[136:137], 1, v[48:49]
	v_lshl_add_u64 v[48:49], v[48:49], 0, v[200:201]
	v_mov_b32_e32 v192, v46
	v_mov_b32_e32 v193, v47
	s_waitcnt vmcnt(12)
	v_lshlrev_b32_e32 v46, 16, v92
	v_and_b32_e32 v47, 0xffff0000, v92
	v_lshlrev_b32_e32 v50, 16, v93
	v_and_b32_e32 v51, 0xffff0000, v93
	v_pk_add_f32 v[44:45], v[44:45], v[50:51]
	v_pk_add_f32 v[42:43], v[42:43], v[46:47]
	v_mul_f32_e32 v47, v45, v45
	v_mul_f32_e32 v46, v43, v43
	v_fmac_f32_e32 v46, v42, v42
	v_fmac_f32_e32 v47, v44, v44
	v_add_f32_e32 v52, v52, v53
	v_add_f32_e32 v46, v46, v47
	v_add_f32_e32 v52, v52, v46
	s_waitcnt vmcnt(11)
	v_lshlrev_b32_e32 v46, 16, v90
	v_and_b32_e32 v47, 0xffff0000, v90
	v_lshlrev_b32_e32 v50, 16, v91
	v_and_b32_e32 v51, 0xffff0000, v91
	v_pk_add_f32 v[40:41], v[40:41], v[50:51]
	v_pk_add_f32 v[38:39], v[38:39], v[46:47]
	v_cvt_pk_bf16_f32 v42, v42, v43
	v_mul_f32_e32 v46, v41, v41
	v_mul_f32_e32 v43, v39, v39
	v_fmac_f32_e32 v43, v38, v38
	v_fmac_f32_e32 v46, v40, v40
	v_add_f32_e32 v43, v43, v46
	s_waitcnt vmcnt(10)
	v_lshlrev_b32_e32 v46, 16, v88
	v_and_b32_e32 v47, 0xffff0000, v88
	v_lshlrev_b32_e32 v50, 16, v89
	v_and_b32_e32 v51, 0xffff0000, v89
	v_pk_add_f32 v[36:37], v[36:37], v[50:51]
	v_pk_add_f32 v[46:47], v[34:35], v[46:47]
	v_mul_f32_e32 v35, v37, v37
	v_mul_f32_e32 v34, v47, v47
	v_fmac_f32_e32 v34, v46, v46
	v_fmac_f32_e32 v35, v36, v36
	v_add_f32_e32 v43, v52, v43
	v_add_f32_e32 v34, v34, v35
	v_add_f32_e32 v34, v43, v34
	v_mov_b32_e32 v35, v34
	s_nop 1
	v_permlane16_swap_b32_e32 v35, v34
	v_cvt_pk_bf16_f32 v43, v44, v45
	v_mov_b32_e32 v194, v42
	v_mov_b32_e32 v195, v43
	s_nop 1
	v_permlane16_swap_b32_e32 v192, v194
	v_permlane16_swap_b32_e32 v193, v195
	global_store_dwordx4 v[48:49], v[192:195], off
	v_cvt_pk_bf16_f32 v38, v38, v39
	v_cvt_pk_bf16_f32 v39, v40, v41
	s_waitcnt lgkmcnt(0)
	v_add_f32_e32 v34, v34, v35
	ds_bpermute_b32 v35, v115, v34
	v_mov_b32_e32 v196, v38
	v_mov_b32_e32 v197, v39
	v_cvt_pk_bf16_f32 v38, v46, v47
	v_cvt_pk_bf16_f32 v39, v36, v37
	v_mov_b32_e32 v198, v38
	v_mov_b32_e32 v199, v39
	s_nop 1
	v_permlane16_swap_b32_e32 v196, v198
	v_permlane16_swap_b32_e32 v197, v199
	global_store_dwordx4 v[48:49], v[196:199], off offset:256
	s_and_saveexec_b64 s[78:79], s[6:7]
	s_cbranch_execz .LBB0_1278
	v_lshlrev_b64 v[36:37], 6, v[84:85]
	v_lshl_add_u64 v[36:37], s[14:15], 0, v[36:37]
	v_lshl_add_u64 v[36:37], s[76:77], 2, v[36:37]
	s_lshl_b32 s64, s86, 2
	v_lshl_add_u64 v[36:37], v[36:37], 0, s[64:65]
	s_waitcnt lgkmcnt(0)
	v_add_f32_e32 v34, v34, v35
	global_store_dword v[36:37], v34, off
; __device__ __forceinline__ unsigned cvt_pk_bf16(float lo, float hi) { unsigned r; asm volatile("v_cvt_pk_bf16_f32 %0, %1, %2" : "=v"(r) : "v"(lo), "v"(hi)); return r; }
;     __device__ __forceinline__ void operator()(f32x4 (&acc)[2][2][4][2], const Unit& u, int wr, int wc, int fr, int fq) const {
;     ...
;             for (int m = 0; m < 4; ++m) { const int row = u.pm * BM + ai * HALF + wr * 64 + m * 16 + fr; const size_t off = (size_t)row * ldc + col0; float sq = 0.f;
; #pragma unroll
;                 for (int bj = 0; bj < 2; ++bj)
; #pragma unroll
;                     for (int n = 0; n < 2; ++n) { const unsigned long long b = old[m][bj][n];
;                         const unsigned blo = (unsigned)b, bhi = (unsigned)(b >> 32);
;                         f32x4 v; v[0] = __builtin_bit_cast(float, blo << 16); v[1] = __builtin_bit_cast(float, blo & 0xffff0000u); v[2] = __builtin_bit_cast(float, bhi << 16); v[3] = __builtin_bit_cast(float, bhi & 0xffff0000u);
;                         v = v + acc[ai][bj][m][n];
;                         sq += (v[0] * v[0] + v[1] * v[1]) + (v[2] * v[2] + v[3] * v[3]);
;                         *(unsigned long long*)(xb + off + bj * HALF + n * 16) = (unsigned long long)cvt_pk_bf16(v[0], v[1]) | ((unsigned long long)cvt_pk_bf16(v[2], v[3]) << 32); }
;                 sq += __shfl_xor(sq, 16); sq += __shfl_xor(sq, 32);
;                 if (fq == 0) ssp[(size_t)row * 16 + 4 * u.pn + wc] = sq; }
.LBB0_1278:
	s_or_b64 exec, exec, s[78:79]
	s_waitcnt vmcnt(11)
	v_lshlrev_b32_e32 v36, 16, v86
	v_and_b32_e32 v37, 0xffff0000, v86
	v_lshlrev_b32_e32 v38, 16, v87
	v_and_b32_e32 v39, 0xffff0000, v87
	v_pk_add_f32 v[32:33], v[32:33], v[38:39]
	v_pk_add_f32 v[30:31], v[30:31], v[36:37]
	s_waitcnt lgkmcnt(0)
	v_lshlrev_b64 v[34:35], 10, v[70:71]
	v_mul_f32_e32 v36, v31, v31
	v_mul_f32_e32 v37, v33, v33
	v_fmac_f32_e32 v36, v30, v30
	v_fmac_f32_e32 v37, v32, v32
	v_cvt_pk_bf16_f32 v30, v30, v31
	v_cvt_pk_bf16_f32 v31, v32, v33
	v_lshl_add_u64 v[32:33], v[34:35], 1, s[42:43]
	v_lshl_add_u64 v[32:33], v[136:137], 1, v[32:33]
	v_lshl_add_u64 v[32:33], v[32:33], 0, v[200:201]
	v_mov_b32_e32 v192, v30
	v_mov_b32_e32 v193, v31
	s_waitcnt vmcnt(10)
	v_lshlrev_b32_e32 v30, 16, v82
	v_and_b32_e32 v31, 0xffff0000, v82
	v_lshlrev_b32_e32 v34, 16, v83
	v_and_b32_e32 v35, 0xffff0000, v83
	v_pk_add_f32 v[28:29], v[28:29], v[34:35]
	v_pk_add_f32 v[26:27], v[26:27], v[30:31]
	v_mul_f32_e32 v31, v29, v29
	v_mul_f32_e32 v30, v27, v27
	v_fmac_f32_e32 v30, v26, v26
	v_fmac_f32_e32 v31, v28, v28
	v_add_f32_e32 v36, v36, v37
	v_add_f32_e32 v30, v30, v31
	v_add_f32_e32 v36, v36, v30
	s_waitcnt vmcnt(9)
	v_lshlrev_b32_e32 v30, 16, v78
	v_and_b32_e32 v31, 0xffff0000, v78
	v_lshlrev_b32_e32 v34, 16, v79
	v_and_b32_e32 v35, 0xffff0000, v79
	v_pk_add_f32 v[24:25], v[24:25], v[34:35]
	v_pk_add_f32 v[22:23], v[22:23], v[30:31]
	v_cvt_pk_bf16_f32 v26, v26, v27
	v_mul_f32_e32 v30, v25, v25
	v_mul_f32_e32 v27, v23, v23
	v_fmac_f32_e32 v27, v22, v22
	v_fmac_f32_e32 v30, v24, v24
	v_add_f32_e32 v27, v27, v30
	s_waitcnt vmcnt(8)
	v_lshlrev_b32_e32 v30, 16, v74
	v_and_b32_e32 v31, 0xffff0000, v74
	v_lshlrev_b32_e32 v34, 16, v75
	v_and_b32_e32 v35, 0xffff0000, v75
	v_pk_add_f32 v[20:21], v[20:21], v[34:35]
	v_pk_add_f32 v[30:31], v[18:19], v[30:31]
	v_mul_f32_e32 v19, v21, v21
	v_mul_f32_e32 v18, v31, v31
	v_fmac_f32_e32 v18, v30, v30
	v_fmac_f32_e32 v19, v20, v20
	v_add_f32_e32 v27, v36, v27
	v_add_f32_e32 v18, v18, v19
	v_add_f32_e32 v18, v27, v18
	v_mov_b32_e32 v19, v18
	s_nop 1
	v_permlane16_swap_b32_e32 v19, v18
	v_cvt_pk_bf16_f32 v27, v28, v29
	v_mov_b32_e32 v194, v26
	v_mov_b32_e32 v195, v27
	s_nop 1
	v_permlane16_swap_b32_e32 v192, v194
	v_permlane16_swap_b32_e32 v193, v195
	global_store_dwordx4 v[32:33], v[192:195], off
	v_cvt_pk_bf16_f32 v22, v22, v23
	v_cvt_pk_bf16_f32 v23, v24, v25
	s_waitcnt lgkmcnt(0)
	v_add_f32_e32 v18, v18, v19
	ds_bpermute_b32 v19, v115, v18
	v_mov_b32_e32 v196, v22
	v_mov_b32_e32 v197, v23
	v_cvt_pk_bf16_f32 v22, v30, v31
	v_cvt_pk_bf16_f32 v23, v20, v21
	v_mov_b32_e32 v198, v22
	v_mov_b32_e32 v199, v23
	s_nop 1
	v_permlane16_swap_b32_e32 v196, v198
	v_permlane16_swap_b32_e32 v197, v199
	global_store_dwordx4 v[32:33], v[196:199], off offset:256
	s_and_saveexec_b64 s[78:79], s[6:7]
	s_cbranch_execz .LBB0_1280
	v_lshlrev_b64 v[20:21], 6, v[70:71]
	v_lshl_add_u64 v[20:21], s[14:15], 0, v[20:21]
	v_lshl_add_u64 v[20:21], s[76:77], 2, v[20:21]
	s_lshl_b32 s64, s86, 2
	v_lshl_add_u64 v[20:21], v[20:21], 0, s[64:65]
	s_waitcnt lgkmcnt(0)
	v_add_f32_e32 v18, v18, v19
	global_store_dword v[20:21], v18, off
.LBB0_1280:
	s_or_b64 exec, exec, s[78:79]
	s_waitcnt vmcnt(9)
	v_lshlrev_b32_e32 v20, 16, v80
	v_and_b32_e32 v21, 0xffff0000, v80
	v_lshlrev_b32_e32 v22, 16, v81
	v_and_b32_e32 v23, 0xffff0000, v81
	v_pk_add_f32 v[16:17], v[16:17], v[22:23]
	v_pk_add_f32 v[14:15], v[14:15], v[20:21]
	s_waitcnt lgkmcnt(0)
	v_lshlrev_b64 v[18:19], 10, v[66:67]
	v_mul_f32_e32 v20, v15, v15
	v_mul_f32_e32 v21, v17, v17
	v_fmac_f32_e32 v20, v14, v14
	v_fmac_f32_e32 v21, v16, v16
	v_cvt_pk_bf16_f32 v14, v14, v15
	v_cvt_pk_bf16_f32 v15, v16, v17
	v_lshl_add_u64 v[16:17], v[18:19], 1, s[42:43]
	v_lshl_add_u64 v[16:17], v[136:137], 1, v[16:17]
	v_lshl_add_u64 v[16:17], v[16:17], 0, v[200:201]
	v_mov_b32_e32 v192, v14
	v_mov_b32_e32 v193, v15
	s_waitcnt vmcnt(9)
	v_lshlrev_b32_e32 v14, 16, v76
	v_and_b32_e32 v15, 0xffff0000, v76
	v_lshlrev_b32_e32 v18, 16, v77
	v_and_b32_e32 v19, 0xffff0000, v77
	v_pk_add_f32 v[12:13], v[12:13], v[18:19]
	v_pk_add_f32 v[10:11], v[10:11], v[14:15]
	v_mul_f32_e32 v15, v13, v13
	v_mul_f32_e32 v14, v11, v11
	v_fmac_f32_e32 v14, v10, v10
	v_fmac_f32_e32 v15, v12, v12
	v_add_f32_e32 v20, v20, v21
	v_add_f32_e32 v14, v14, v15
	v_add_f32_e32 v20, v20, v14
	s_waitcnt vmcnt(8)
	v_lshlrev_b32_e32 v14, 16, v72
	v_and_b32_e32 v15, 0xffff0000, v72
	v_lshlrev_b32_e32 v18, 16, v73
	v_and_b32_e32 v19, 0xffff0000, v73
	v_pk_add_f32 v[8:9], v[8:9], v[18:19]
	v_pk_add_f32 v[6:7], v[6:7], v[14:15]
	v_cvt_pk_bf16_f32 v10, v10, v11
	v_mul_f32_e32 v14, v9, v9
	v_mul_f32_e32 v11, v7, v7
	v_fmac_f32_e32 v11, v6, v6
	v_fmac_f32_e32 v14, v8, v8
	v_add_f32_e32 v11, v11, v14
	s_waitcnt vmcnt(8)
	v_lshlrev_b32_e32 v14, 16, v68
	v_and_b32_e32 v15, 0xffff0000, v68
	v_lshlrev_b32_e32 v18, 16, v69
	v_and_b32_e32 v19, 0xffff0000, v69
	v_pk_add_f32 v[4:5], v[4:5], v[18:19]
	v_pk_add_f32 v[14:15], v[2:3], v[14:15]
	v_mul_f32_e32 v3, v5, v5
	v_mul_f32_e32 v2, v15, v15
	v_fmac_f32_e32 v2, v14, v14
	v_fmac_f32_e32 v3, v4, v4
	v_add_f32_e32 v11, v20, v11
	v_add_f32_e32 v2, v2, v3
	v_add_f32_e32 v2, v11, v2
	v_mov_b32_e32 v3, v2
	s_nop 1
	v_permlane16_swap_b32_e32 v3, v2
	v_cvt_pk_bf16_f32 v11, v12, v13
	v_mov_b32_e32 v194, v10
	v_mov_b32_e32 v195, v11
	s_nop 1
	v_permlane16_swap_b32_e32 v192, v194
	v_permlane16_swap_b32_e32 v193, v195
	global_store_dwordx4 v[16:17], v[192:195], off
	v_cvt_pk_bf16_f32 v6, v6, v7
	v_cvt_pk_bf16_f32 v7, v8, v9
	s_waitcnt lgkmcnt(0)
	v_add_f32_e32 v2, v2, v3
	ds_bpermute_b32 v3, v115, v2
	v_mov_b32_e32 v196, v6
	v_mov_b32_e32 v197, v7
	v_cvt_pk_bf16_f32 v6, v14, v15
	v_cvt_pk_bf16_f32 v7, v4, v5
	v_mov_b32_e32 v198, v6
	v_mov_b32_e32 v199, v7
	s_nop 1
	v_permlane16_swap_b32_e32 v196, v198
	v_permlane16_swap_b32_e32 v197, v199
	global_store_dwordx4 v[16:17], v[196:199], off offset:256
	s_and_saveexec_b64 s[78:79], s[6:7]
	s_cbranch_execz .LBB0_1282
	v_lshlrev_b64 v[4:5], 6, v[66:67]
	v_lshl_add_u64 v[4:5], s[14:15], 0, v[4:5]
	v_lshl_add_u64 v[4:5], s[76:77], 2, v[4:5]
	s_lshl_b32 s64, s86, 2
	v_lshl_add_u64 v[4:5], v[4:5], 0, s[64:65]
	s_waitcnt lgkmcnt(0)
	v_add_f32_e32 v2, v2, v3
	global_store_dword v[4:5], v2, off

; __device__ __forceinline__ unsigned cvt_pk_bf16(float lo, float hi) { unsigned r; asm volatile("v_cvt_pk_bf16_f32 %0, %1, %2" : "=v"(r) : "v"(lo), "v"(hi)); return r; }
;     __device__ __forceinline__ void operator()(f32x4 (&acc)[2][2][4][2], const Unit& u, int wr, int wc, int fr, int fq) const {
;         const int col0 = u.pn * BM + wc * 32 + 4 * fq;
; #pragma unroll
;         for (int ai = 0; ai < 2; ++ai) {
;             unsigned long long old[4][2][2];
; #pragma unroll
;             for (int m = 0; m < 4; ++m) { const size_t off = (size_t)(u.pm * BM + ai * HALF + wr * 64 + m * 16 + fr) * ldc + col0;
; #pragma unroll
;                 for (int bj = 0; bj < 2; ++bj)
; #pragma unroll
;                     for (int n = 0; n < 2; ++n) old[m][bj][n] = *(const unsigned long long*)(xb + off + bj * HALF + n * 16); }
; #pragma unroll
;             for (int m = 0; m < 4; ++m) { const int row = u.pm * BM + ai * HALF + wr * 64 + m * 16 + fr; const size_t off = (size_t)row * ldc + col0; float sq = 0.f;
; #pragma unroll
;                 for (int bj = 0; bj < 2; ++bj)
; #pragma unroll
;                     for (int n = 0; n < 2; ++n) { const unsigned long long b = old[m][bj][n];
;                         const unsigned blo = (unsigned)b, bhi = (unsigned)(b >> 32);
;                         f32x4 v; v[0] = __builtin_bit_cast(float, blo << 16); v[1] = __builtin_bit_cast(float, blo & 0xffff0000u); v[2] = __builtin_bit_cast(float, bhi << 16); v[3] = __builtin_bit_cast(float, bhi & 0xffff0000u);
;                         v = v + acc[ai][bj][m][n];
;                         sq += (v[0] * v[0] + v[1] * v[1]) + (v[2] * v[2] + v[3] * v[3]);
;                         *(unsigned long long*)(xb + off + bj * HALF + n * 16) = (unsigned long long)cvt_pk_bf16(v[0], v[1]) | ((unsigned long long)cvt_pk_bf16(v[2], v[3]) << 32); }
;                 sq += __shfl_xor(sq, 16); sq += __shfl_xor(sq, 32);
;                 if (fq == 0) ssp[(size_t)row * 16 + 4 * u.pn + wc] = sq; }
.LBB0_1515:
	v_bfe_u32 v200, v229, 4, 1
	v_mul_u32_u24_e32 v200, 24, v200
	v_mov_b32_e32 v201, 0
	v_lshl_or_b32 v136, s12, 8, v174
	v_lshl_add_u32 v140, s13, 8, v172
	v_ashrrev_i32_e32 v137, 31, v136
	v_lshlrev_b64 v[176:177], 1, v[136:137]
	v_ashrrev_i32_e32 v141, 31, v140
	v_lshl_add_u64 v[138:139], s[42:43], 0, v[176:177]
	v_lshlrev_b64 v[178:179], 11, v[140:141]
	v_lshl_add_u64 v[142:143], v[138:139], 0, v[178:179]
	global_load_dwordx2 v[180:181], v[142:143], off
	global_load_dwordx2 v[182:183], v[142:143], off offset:32
	global_load_dwordx2 v[184:185], v[142:143], off offset:256
	global_load_dwordx2 v[188:189], v[142:143], off offset:288
	v_or_b32_e32 v160, 16, v140
	v_ashrrev_i32_e32 v161, 31, v160
	v_lshlrev_b64 v[142:143], 11, v[160:161]
	v_or_b32_e32 v146, 32, v140
	v_lshl_add_u64 v[142:143], v[138:139], 0, v[142:143]
	v_ashrrev_i32_e32 v147, 31, v146
	global_load_dwordx2 v[170:171], v[142:143], off
	global_load_dwordx2 v[168:169], v[142:143], off offset:32
	global_load_dwordx2 v[166:167], v[142:143], off offset:256
	global_load_dwordx2 v[164:165], v[142:143], off offset:288
	v_lshlrev_b64 v[142:143], 11, v[146:147]
	v_lshl_add_u64 v[142:143], v[138:139], 0, v[142:143]
	global_load_dwordx2 v[162:163], v[142:143], off
	global_load_dwordx2 v[158:159], v[142:143], off offset:32
	global_load_dwordx2 v[154:155], v[142:143], off offset:256
	global_load_dwordx2 v[150:151], v[142:143], off offset:288
	v_or_b32_e32 v142, 48, v140
	v_ashrrev_i32_e32 v143, 31, v142
	v_lshlrev_b64 v[144:145], 11, v[142:143]
	v_lshl_add_u64 v[144:145], v[138:139], 0, v[144:145]
	global_load_dwordx2 v[156:157], v[144:145], off
	global_load_dwordx2 v[152:153], v[144:145], off offset:32
	global_load_dwordx2 v[148:149], v[144:145], off offset:256
	s_nop 0
	global_load_dwordx2 v[144:145], v[144:145], off offset:288
	s_lshl_b32 s72, s12, 2
	s_ashr_i32 s73, s72, 31
	s_waitcnt vmcnt(0)
	s_mov_b32 s100, 1
	v_lshlrev_b32_e32 v190, 16, v180
	v_and_b32_e32 v191, 0xffff0000, v180
	v_lshlrev_b32_e32 v180, 16, v181
	v_and_b32_e32 v181, 0xffff0000, v181
	v_pk_add_f32 v[128:129], v[128:129], v[180:181]
	v_pk_add_f32 v[126:127], v[126:127], v[190:191]
	v_mul_f32_e32 v181, v129, v129
	v_mul_f32_e32 v180, v127, v127
	v_fmac_f32_e32 v180, v126, v126
	v_fmac_f32_e32 v181, v128, v128
	v_cvt_pk_bf16_f32 v126, v126, v127
	v_cvt_pk_bf16_f32 v127, v128, v129
	v_lshl_add_u64 v[128:129], s[42:43], 0, v[178:179]
	v_lshl_add_u64 v[128:129], v[128:129], 0, v[176:177]
	v_lshl_add_u64 v[128:129], v[128:129], 0, v[200:201]
	v_mov_b32_e32 v192, v126
	v_mov_b32_e32 v193, v127
	v_lshlrev_b32_e32 v126, 16, v182
	v_and_b32_e32 v127, 0xffff0000, v182
	v_pk_add_f32 v[122:123], v[122:123], v[126:127]
	v_lshlrev_b32_e32 v176, 16, v183
	v_and_b32_e32 v177, 0xffff0000, v183
	v_mul_f32_e32 v126, v123, v123
	v_pk_add_f32 v[124:125], v[124:125], v[176:177]
	v_fmac_f32_e32 v126, v122, v122
	v_cvt_pk_bf16_f32 v122, v122, v123
	v_cvt_pk_bf16_f32 v123, v124, v125
	v_mul_f32_e32 v127, v125, v125
	v_mov_b32_e32 v194, v122
	v_mov_b32_e32 v195, v123
	s_nop 1
	v_permlane16_swap_b32_e32 v192, v194
	v_permlane16_swap_b32_e32 v193, v195
	global_store_dwordx4 v[128:129], v[192:195], off
	v_lshlrev_b32_e32 v122, 16, v184
	v_and_b32_e32 v123, 0xffff0000, v184
	v_fmac_f32_e32 v127, v124, v124
	v_lshlrev_b32_e32 v124, 16, v185
	v_and_b32_e32 v125, 0xffff0000, v185
	v_pk_add_f32 v[118:119], v[118:119], v[122:123]
	v_pk_add_f32 v[120:121], v[120:121], v[124:125]
	v_mul_f32_e32 v122, v119, v119
	v_fmac_f32_e32 v122, v118, v118
	v_mul_f32_e32 v123, v121, v121
	v_cvt_pk_bf16_f32 v118, v118, v119
	v_cvt_pk_bf16_f32 v119, v120, v121
	v_fmac_f32_e32 v123, v120, v120
	v_mov_b32_e32 v196, v118
	v_mov_b32_e32 v197, v119
	v_lshlrev_b32_e32 v118, 16, v188
	v_and_b32_e32 v119, 0xffff0000, v188
	v_lshlrev_b32_e32 v120, 16, v189
	v_and_b32_e32 v121, 0xffff0000, v189
	v_pk_add_f32 v[116:117], v[116:117], v[120:121]
	v_pk_add_f32 v[118:119], v[114:115], v[118:119]
	v_add_f32_e32 v180, v180, v181
	v_add_f32_e32 v126, v126, v127
	v_mul_f32_e32 v114, v119, v119
	v_mul_f32_e32 v115, v117, v117
	v_add_f32_e32 v126, v180, v126
	v_add_f32_e32 v122, v122, v123
	v_fmac_f32_e32 v114, v118, v118
	v_fmac_f32_e32 v115, v116, v116
	v_add_f32_e32 v122, v126, v122
	v_add_f32_e32 v114, v114, v115
	v_cvt_pk_bf16_f32 v118, v118, v119
	v_cvt_pk_bf16_f32 v119, v116, v117
	v_and_b32_e32 v116, 64, v229
	v_add_f32_e32 v115, v122, v114
	v_xor_b32_e32 v114, 16, v229
	v_add_u32_e32 v117, 64, v116
	v_cmp_lt_i32_e32 vcc, v114, v117
	v_mov_b32_e32 v198, v118
	v_mov_b32_e32 v199, v119
	s_nop 1
	v_permlane16_swap_b32_e32 v196, v198
	v_permlane16_swap_b32_e32 v197, v199
	global_store_dwordx4 v[128:129], v[196:199], off offset:256
	s_nop 0
	v_cndmask_b32_e32 v114, v229, v114, vcc
	v_lshlrev_b32_e32 v114, 2, v114
	v_mov_b32_e32 v116, v115
	s_nop 1
	v_permlane16_swap_b32_e32 v116, v115
	s_waitcnt lgkmcnt(0)
	v_add_f32_e32 v116, v115, v116
	v_xor_b32_e32 v115, 32, v229
	v_cmp_lt_i32_e32 vcc, v115, v117
	s_nop 1
	v_cndmask_b32_e32 v115, v229, v115, vcc
	v_lshlrev_b32_e32 v115, 2, v115
	ds_bpermute_b32 v117, v115, v116
	s_and_saveexec_b64 s[74:75], s[4:5]
	s_cbranch_execz .LBB0_1517
	v_readlane_b32 s12, v253, 38
	v_lshlrev_b64 v[118:119], 6, v[140:141]
	v_readlane_b32 s13, v253, 39
	s_lshl_b32 s64, s82, 2
	s_waitcnt lgkmcnt(0)
	v_add_f32_e32 v116, v116, v117
	v_lshl_add_u64 v[118:119], s[12:13], 0, v[118:119]
	v_lshl_add_u64 v[118:119], s[72:73], 2, v[118:119]
	v_lshl_add_u64 v[118:119], v[118:119], 0, s[64:65]
	global_store_dword v[118:119], v116, off
; __device__ __forceinline__ unsigned cvt_pk_bf16(float lo, float hi) { unsigned r; asm volatile("v_cvt_pk_bf16_f32 %0, %1, %2" : "=v"(r) : "v"(lo), "v"(hi)); return r; }
;     __device__ __forceinline__ void operator()(f32x4 (&acc)[2][2][4][2], const Unit& u, int wr, int wc, int fr, int fq) const {
;     ...
;             for (int m = 0; m < 4; ++m) { const int row = u.pm * BM + ai * HALF + wr * 64 + m * 16 + fr; const size_t off = (size_t)row * ldc + col0; float sq = 0.f;
; #pragma unroll
;                 for (int bj = 0; bj < 2; ++bj)
; #pragma unroll
;                     for (int n = 0; n < 2; ++n) { const unsigned long long b = old[m][bj][n];
;                         const unsigned blo = (unsigned)b, bhi = (unsigned)(b >> 32);
;                         f32x4 v; v[0] = __builtin_bit_cast(float, blo << 16); v[1] = __builtin_bit_cast(float, blo & 0xffff0000u); v[2] = __builtin_bit_cast(float, bhi << 16); v[3] = __builtin_bit_cast(float, bhi & 0xffff0000u);
;                         v = v + acc[ai][bj][m][n];
;                         sq += (v[0] * v[0] + v[1] * v[1]) + (v[2] * v[2] + v[3] * v[3]);
;                         *(unsigned long long*)(xb + off + bj * HALF + n * 16) = (unsigned long long)cvt_pk_bf16(v[0], v[1]) | ((unsigned long long)cvt_pk_bf16(v[2], v[3]) << 32); }
;                 sq += __shfl_xor(sq, 16); sq += __shfl_xor(sq, 32);
;                 if (fq == 0) ssp[(size_t)row * 16 + 4 * u.pn + wc] = sq; }
.LBB0_1517:
	s_or_b64 exec, exec, s[74:75]
	v_lshlrev_b32_e32 v118, 16, v170
	v_and_b32_e32 v119, 0xffff0000, v170
	v_lshlrev_b32_e32 v120, 16, v171
	v_and_b32_e32 v121, 0xffff0000, v171
	v_pk_add_f32 v[112:113], v[112:113], v[120:121]
	v_pk_add_f32 v[110:111], v[110:111], v[118:119]
	s_waitcnt lgkmcnt(0)
	v_lshlrev_b64 v[116:117], 10, v[160:161]
	v_mul_f32_e32 v118, v111, v111
	v_mul_f32_e32 v119, v113, v113
	v_fmac_f32_e32 v118, v110, v110
	v_fmac_f32_e32 v119, v112, v112
	v_cvt_pk_bf16_f32 v110, v110, v111
	v_cvt_pk_bf16_f32 v111, v112, v113
	v_lshl_add_u64 v[112:113], v[116:117], 1, s[42:43]
	v_lshl_add_u64 v[112:113], v[136:137], 1, v[112:113]
	v_lshl_add_u64 v[112:113], v[112:113], 0, v[200:201]
	v_mov_b32_e32 v192, v110
	v_mov_b32_e32 v193, v111
	v_lshlrev_b32_e32 v110, 16, v168
	v_and_b32_e32 v111, 0xffff0000, v168
	v_lshlrev_b32_e32 v116, 16, v169
	v_and_b32_e32 v117, 0xffff0000, v169
	v_pk_add_f32 v[108:109], v[108:109], v[116:117]
	v_pk_add_f32 v[106:107], v[106:107], v[110:111]
	v_mul_f32_e32 v111, v109, v109
	v_mul_f32_e32 v110, v107, v107
	v_fmac_f32_e32 v110, v106, v106
	v_fmac_f32_e32 v111, v108, v108
	v_add_f32_e32 v118, v118, v119
	v_add_f32_e32 v110, v110, v111
	v_add_f32_e32 v118, v118, v110
	v_lshlrev_b32_e32 v110, 16, v166
	v_and_b32_e32 v111, 0xffff0000, v166
	v_lshlrev_b32_e32 v116, 16, v167
	v_and_b32_e32 v117, 0xffff0000, v167
	v_pk_add_f32 v[104:105], v[104:105], v[116:117]
	v_pk_add_f32 v[102:103], v[102:103], v[110:111]
	v_cvt_pk_bf16_f32 v106, v106, v107
	v_mul_f32_e32 v110, v105, v105
	v_mul_f32_e32 v107, v103, v103
	v_fmac_f32_e32 v107, v102, v102
	v_fmac_f32_e32 v110, v104, v104
	v_add_f32_e32 v107, v107, v110
	v_lshlrev_b32_e32 v110, 16, v164
	v_and_b32_e32 v111, 0xffff0000, v164
	v_lshlrev_b32_e32 v116, 16, v165
	v_and_b32_e32 v117, 0xffff0000, v165
	v_pk_add_f32 v[100:101], v[100:101], v[116:117]
	v_pk_add_f32 v[110:111], v[98:99], v[110:111]
	v_mul_f32_e32 v99, v101, v101
	v_mul_f32_e32 v98, v111, v111
	v_fmac_f32_e32 v98, v110, v110
	v_fmac_f32_e32 v99, v100, v100
	v_add_f32_e32 v107, v118, v107
	v_add_f32_e32 v98, v98, v99
	v_add_f32_e32 v98, v107, v98
	v_mov_b32_e32 v99, v98
	s_nop 1
	v_permlane16_swap_b32_e32 v99, v98
	v_cvt_pk_bf16_f32 v107, v108, v109
	v_mov_b32_e32 v194, v106
	v_mov_b32_e32 v195, v107
	s_nop 1
	v_permlane16_swap_b32_e32 v192, v194
	v_permlane16_swap_b32_e32 v193, v195
	global_store_dwordx4 v[112:113], v[192:195], off
	v_cvt_pk_bf16_f32 v102, v102, v103
	v_cvt_pk_bf16_f32 v103, v104, v105
	s_waitcnt lgkmcnt(0)
	v_add_f32_e32 v98, v98, v99
	ds_bpermute_b32 v99, v115, v98
	v_mov_b32_e32 v196, v102
	v_mov_b32_e32 v197, v103
	v_cvt_pk_bf16_f32 v102, v110, v111
	v_cvt_pk_bf16_f32 v103, v100, v101
	v_mov_b32_e32 v198, v102
	v_mov_b32_e32 v199, v103
	s_nop 1
	v_permlane16_swap_b32_e32 v196, v198
	v_permlane16_swap_b32_e32 v197, v199
	global_store_dwordx4 v[112:113], v[196:199], off offset:256
	s_and_saveexec_b64 s[74:75], s[4:5]
	s_cbranch_execz .LBB0_1519
	v_readlane_b32 s12, v253, 38
	v_lshlrev_b64 v[100:101], 6, v[160:161]
	v_readlane_b32 s13, v253, 39
	s_lshl_b32 s64, s82, 2
	s_waitcnt lgkmcnt(0)
	v_add_f32_e32 v98, v98, v99
	v_lshl_add_u64 v[100:101], s[12:13], 0, v[100:101]
	v_lshl_add_u64 v[100:101], s[72:73], 2, v[100:101]
	v_lshl_add_u64 v[100:101], v[100:101], 0, s[64:65]
	global_store_dword v[100:101], v98, off
.LBB0_1519:
	s_or_b64 exec, exec, s[74:75]
	v_lshlrev_b32_e32 v100, 16, v162
	v_and_b32_e32 v101, 0xffff0000, v162
	v_lshlrev_b32_e32 v102, 16, v163
	v_and_b32_e32 v103, 0xffff0000, v163
	v_pk_add_f32 v[96:97], v[96:97], v[102:103]
	v_pk_add_f32 v[94:95], v[94:95], v[100:101]
	s_waitcnt lgkmcnt(0)
	v_lshlrev_b64 v[98:99], 10, v[146:147]
	v_mul_f32_e32 v100, v95, v95
	v_mul_f32_e32 v101, v97, v97
	v_fmac_f32_e32 v100, v94, v94
	v_fmac_f32_e32 v101, v96, v96
	v_cvt_pk_bf16_f32 v94, v94, v95
	v_cvt_pk_bf16_f32 v95, v96, v97
	v_lshl_add_u64 v[96:97], v[98:99], 1, s[42:43]
	v_lshl_add_u64 v[96:97], v[136:137], 1, v[96:97]
	v_lshl_add_u64 v[96:97], v[96:97], 0, v[200:201]
	v_mov_b32_e32 v192, v94
	v_mov_b32_e32 v193, v95
	v_lshlrev_b32_e32 v94, 16, v158
	v_and_b32_e32 v95, 0xffff0000, v158
	v_lshlrev_b32_e32 v98, 16, v159
	v_and_b32_e32 v99, 0xffff0000, v159
	v_pk_add_f32 v[92:93], v[92:93], v[98:99]
	v_pk_add_f32 v[90:91], v[90:91], v[94:95]
	v_mul_f32_e32 v95, v93, v93
	v_mul_f32_e32 v94, v91, v91
	v_fmac_f32_e32 v94, v90, v90
	v_fmac_f32_e32 v95, v92, v92
	v_add_f32_e32 v100, v100, v101
	v_add_f32_e32 v94, v94, v95
	v_add_f32_e32 v100, v100, v94
	v_lshlrev_b32_e32 v94, 16, v154
	v_and_b32_e32 v95, 0xffff0000, v154
	v_lshlrev_b32_e32 v98, 16, v155
	v_and_b32_e32 v99, 0xffff0000, v155
	v_pk_add_f32 v[88:89], v[88:89], v[98:99]
	v_pk_add_f32 v[86:87], v[86:87], v[94:95]
	v_cvt_pk_bf16_f32 v90, v90, v91
	v_mul_f32_e32 v94, v89, v89
	v_mul_f32_e32 v91, v87, v87
	v_fmac_f32_e32 v91, v86, v86
	v_fmac_f32_e32 v94, v88, v88
	v_add_f32_e32 v91, v91, v94
	v_lshlrev_b32_e32 v94, 16, v150
	v_and_b32_e32 v95, 0xffff0000, v150
	v_lshlrev_b32_e32 v98, 16, v151
	v_and_b32_e32 v99, 0xffff0000, v151
	v_pk_add_f32 v[84:85], v[84:85], v[98:99]
	v_pk_add_f32 v[94:95], v[82:83], v[94:95]
	v_mul_f32_e32 v83, v85, v85
	v_mul_f32_e32 v82, v95, v95
	v_fmac_f32_e32 v82, v94, v94
	v_fmac_f32_e32 v83, v84, v84
	v_add_f32_e32 v91, v100, v91
	v_add_f32_e32 v82, v82, v83
	v_add_f32_e32 v82, v91, v82
	v_mov_b32_e32 v83, v82
	s_nop 1
	v_permlane16_swap_b32_e32 v83, v82
	v_cvt_pk_bf16_f32 v91, v92, v93
	v_mov_b32_e32 v194, v90
	v_mov_b32_e32 v195, v91
	s_nop 1
	v_permlane16_swap_b32_e32 v192, v194
	v_permlane16_swap_b32_e32 v193, v195
	global_store_dwordx4 v[96:97], v[192:195], off
	v_cvt_pk_bf16_f32 v86, v86, v87
	v_cvt_pk_bf16_f32 v87, v88, v89
	s_waitcnt lgkmcnt(0)
	v_add_f32_e32 v82, v82, v83
	ds_bpermute_b32 v83, v115, v82
	v_mov_b32_e32 v196, v86
	v_mov_b32_e32 v197, v87
	v_cvt_pk_bf16_f32 v86, v94, v95
	v_cvt_pk_bf16_f32 v87, v84, v85
	v_mov_b32_e32 v198, v86
	v_mov_b32_e32 v199, v87
	s_nop 1
	v_permlane16_swap_b32_e32 v196, v198
	v_permlane16_swap_b32_e32 v197, v199
	global_store_dwordx4 v[96:97], v[196:199], off offset:256
	s_and_saveexec_b64 s[74:75], s[4:5]
	v_readlane_b32 s54, v255, 28
	v_readlane_b32 s55, v255, 29
	s_cbranch_execz .LBB0_1521
	v_readlane_b32 s12, v253, 38
	v_lshlrev_b64 v[84:85], 6, v[146:147]
	v_readlane_b32 s13, v253, 39
	s_lshl_b32 s64, s82, 2
	s_waitcnt lgkmcnt(0)
	v_add_f32_e32 v82, v82, v83
	v_lshl_add_u64 v[84:85], s[12:13], 0, v[84:85]
	v_lshl_add_u64 v[84:85], s[72:73], 2, v[84:85]
	v_lshl_add_u64 v[84:85], v[84:85], 0, s[64:65]
	global_store_dword v[84:85], v82, off
; __device__ __forceinline__ unsigned cvt_pk_bf16(float lo, float hi) { unsigned r; asm volatile("v_cvt_pk_bf16_f32 %0, %1, %2" : "=v"(r) : "v"(lo), "v"(hi)); return r; }
;     __device__ __forceinline__ void operator()(f32x4 (&acc)[2][2][4][2], const Unit& u, int wr, int wc, int fr, int fq) const {
;     ...
;             for (int m = 0; m < 4; ++m) { const size_t off = (size_t)(u.pm * BM + ai * HALF + wr * 64 + m * 16 + fr) * ldc + col0;
; #pragma unroll
;                 for (int bj = 0; bj < 2; ++bj)
; #pragma unroll
;                     for (int n = 0; n < 2; ++n) old[m][bj][n] = *(const unsigned long long*)(xb + off + bj * HALF + n * 16); }
; #pragma unroll
;             for (int m = 0; m < 4; ++m) { const int row = u.pm * BM + ai * HALF + wr * 64 + m * 16 + fr; const size_t off = (size_t)row * ldc + col0; float sq = 0.f;
; #pragma unroll
;                 for (int bj = 0; bj < 2; ++bj)
; #pragma unroll
;                     for (int n = 0; n < 2; ++n) { const unsigned long long b = old[m][bj][n];
;                         const unsigned blo = (unsigned)b, bhi = (unsigned)(b >> 32);
;                         f32x4 v; v[0] = __builtin_bit_cast(float, blo << 16); v[1] = __builtin_bit_cast(float, blo & 0xffff0000u); v[2] = __builtin_bit_cast(float, bhi << 16); v[3] = __builtin_bit_cast(float, bhi & 0xffff0000u);
;                         v = v + acc[ai][bj][m][n];
;                         sq += (v[0] * v[0] + v[1] * v[1]) + (v[2] * v[2] + v[3] * v[3]);
;                         *(unsigned long long*)(xb + off + bj * HALF + n * 16) = (unsigned long long)cvt_pk_bf16(v[0], v[1]) | ((unsigned long long)cvt_pk_bf16(v[2], v[3]) << 32); }
;                 sq += __shfl_xor(sq, 16); sq += __shfl_xor(sq, 32);
;                 if (fq == 0) ssp[(size_t)row * 16 + 4 * u.pn + wc] = sq; }
.LBB0_1521:
	s_or_b64 exec, exec, s[74:75]
	v_lshlrev_b32_e32 v84, 16, v156
	v_and_b32_e32 v85, 0xffff0000, v156
	v_lshlrev_b32_e32 v86, 16, v157
	v_and_b32_e32 v87, 0xffff0000, v157
	v_pk_add_f32 v[80:81], v[80:81], v[86:87]
	v_pk_add_f32 v[78:79], v[78:79], v[84:85]
	s_waitcnt lgkmcnt(0)
	v_lshlrev_b64 v[82:83], 10, v[142:143]
	v_mul_f32_e32 v84, v79, v79
	v_mul_f32_e32 v85, v81, v81
	v_fmac_f32_e32 v84, v78, v78
	v_fmac_f32_e32 v85, v80, v80
	v_cvt_pk_bf16_f32 v78, v78, v79
	v_cvt_pk_bf16_f32 v79, v80, v81
	v_lshl_add_u64 v[80:81], v[82:83], 1, s[42:43]
	v_lshl_add_u64 v[80:81], v[136:137], 1, v[80:81]
	v_lshl_add_u64 v[80:81], v[80:81], 0, v[200:201]
	v_mov_b32_e32 v192, v78
	v_mov_b32_e32 v193, v79
	v_lshlrev_b32_e32 v78, 16, v152
	v_and_b32_e32 v79, 0xffff0000, v152
	v_lshlrev_b32_e32 v82, 16, v153
	v_and_b32_e32 v83, 0xffff0000, v153
	v_pk_add_f32 v[76:77], v[76:77], v[82:83]
	v_pk_add_f32 v[74:75], v[74:75], v[78:79]
	v_mul_f32_e32 v79, v77, v77
	v_mul_f32_e32 v78, v75, v75
	v_fmac_f32_e32 v78, v74, v74
	v_fmac_f32_e32 v79, v76, v76
	v_add_f32_e32 v84, v84, v85
	v_add_f32_e32 v78, v78, v79
	v_add_f32_e32 v84, v84, v78
	v_lshlrev_b32_e32 v78, 16, v148
	v_and_b32_e32 v79, 0xffff0000, v148
	v_lshlrev_b32_e32 v82, 16, v149
	v_and_b32_e32 v83, 0xffff0000, v149
	v_pk_add_f32 v[72:73], v[72:73], v[82:83]
	v_pk_add_f32 v[70:71], v[70:71], v[78:79]
	v_cvt_pk_bf16_f32 v74, v74, v75
	v_mul_f32_e32 v78, v73, v73
	v_mul_f32_e32 v75, v71, v71
	v_fmac_f32_e32 v75, v70, v70
	v_fmac_f32_e32 v78, v72, v72
	v_add_f32_e32 v75, v75, v78
	v_lshlrev_b32_e32 v78, 16, v144
	v_and_b32_e32 v79, 0xffff0000, v144
	v_lshlrev_b32_e32 v82, 16, v145
	v_and_b32_e32 v83, 0xffff0000, v145
	v_pk_add_f32 v[68:69], v[68:69], v[82:83]
	v_pk_add_f32 v[78:79], v[66:67], v[78:79]
	v_mul_f32_e32 v67, v69, v69
	v_mul_f32_e32 v66, v79, v79
	v_fmac_f32_e32 v66, v78, v78
	v_fmac_f32_e32 v67, v68, v68
	v_add_f32_e32 v75, v84, v75
	v_add_f32_e32 v66, v66, v67
	v_add_f32_e32 v66, v75, v66
	v_mov_b32_e32 v67, v66
	s_nop 1
	v_permlane16_swap_b32_e32 v67, v66
	v_cvt_pk_bf16_f32 v75, v76, v77
	v_mov_b32_e32 v194, v74
	v_mov_b32_e32 v195, v75
	s_nop 1
	v_permlane16_swap_b32_e32 v192, v194
	v_permlane16_swap_b32_e32 v193, v195
	global_store_dwordx4 v[80:81], v[192:195], off
	v_cvt_pk_bf16_f32 v70, v70, v71
	v_cvt_pk_bf16_f32 v71, v72, v73
	s_waitcnt lgkmcnt(0)
	v_add_f32_e32 v66, v66, v67
	ds_bpermute_b32 v67, v115, v66
	v_mov_b32_e32 v196, v70
	v_mov_b32_e32 v197, v71
	v_cvt_pk_bf16_f32 v70, v78, v79
	v_cvt_pk_bf16_f32 v71, v68, v69
	v_mov_b32_e32 v198, v70
	v_mov_b32_e32 v199, v71
	s_nop 1
	v_permlane16_swap_b32_e32 v196, v198
	v_permlane16_swap_b32_e32 v197, v199
	global_store_dwordx4 v[80:81], v[196:199], off offset:256
	s_and_saveexec_b64 s[74:75], s[4:5]
	s_cbranch_execz .LBB0_1523
	v_readlane_b32 s12, v253, 38
	v_lshlrev_b64 v[68:69], 6, v[142:143]
	v_readlane_b32 s13, v253, 39
	s_lshl_b32 s64, s82, 2
	s_waitcnt lgkmcnt(0)
	v_add_f32_e32 v66, v66, v67
	v_lshl_add_u64 v[68:69], s[12:13], 0, v[68:69]
	v_lshl_add_u64 v[68:69], s[72:73], 2, v[68:69]
	v_lshl_add_u64 v[68:69], v[68:69], 0, s[64:65]
	global_store_dword v[68:69], v66, off
.LBB0_1523:
	s_or_b64 exec, exec, s[74:75]
	v_add_u32_e32 v96, 0x80, v140
	v_ashrrev_i32_e32 v97, 31, v96
	v_lshlrev_b64 v[102:103], 11, v[96:97]
	s_waitcnt lgkmcnt(0)
	v_lshl_add_u64 v[66:67], v[138:139], 0, v[102:103]
	global_load_dwordx2 v[104:105], v[66:67], off
	global_load_dwordx2 v[106:107], v[66:67], off offset:32
	global_load_dwordx2 v[100:101], v[66:67], off offset:256
	global_load_dwordx2 v[98:99], v[66:67], off offset:288
	v_add_u32_e32 v84, 0x90, v140
	v_ashrrev_i32_e32 v85, 31, v84
	v_lshlrev_b64 v[66:67], 11, v[84:85]
	v_add_u32_e32 v70, 0xa0, v140
	v_lshl_add_u64 v[66:67], v[138:139], 0, v[66:67]
	v_ashrrev_i32_e32 v71, 31, v70
	global_load_dwordx2 v[94:95], v[66:67], off
	global_load_dwordx2 v[92:93], v[66:67], off offset:32
	global_load_dwordx2 v[90:91], v[66:67], off offset:256
	global_load_dwordx2 v[88:89], v[66:67], off offset:288
	v_lshlrev_b64 v[66:67], 11, v[70:71]
	v_lshl_add_u64 v[66:67], v[138:139], 0, v[66:67]
	global_load_dwordx2 v[86:87], v[66:67], off
	global_load_dwordx2 v[82:83], v[66:67], off offset:32
	global_load_dwordx2 v[78:79], v[66:67], off offset:256
	global_load_dwordx2 v[74:75], v[66:67], off offset:288
	v_add_u32_e32 v66, 0xb0, v140
	v_ashrrev_i32_e32 v67, 31, v66
	v_lshlrev_b64 v[68:69], 11, v[66:67]
	v_lshl_add_u64 v[68:69], v[138:139], 0, v[68:69]
	global_load_dwordx2 v[80:81], v[68:69], off
	global_load_dwordx2 v[76:77], v[68:69], off offset:32
	global_load_dwordx2 v[72:73], v[68:69], off offset:256
	s_nop 0
	global_load_dwordx2 v[68:69], v[68:69], off offset:288
	s_waitcnt vmcnt(15)
	v_lshlrev_b32_e32 v108, 16, v104
	v_and_b32_e32 v109, 0xffff0000, v104
	v_lshlrev_b32_e32 v104, 16, v105
	v_and_b32_e32 v105, 0xffff0000, v105
	v_pk_add_f32 v[64:65], v[64:65], v[104:105]
	v_pk_add_f32 v[62:63], v[62:63], v[108:109]
	v_mul_f32_e32 v105, v65, v65
	v_mul_f32_e32 v104, v63, v63
	v_fmac_f32_e32 v104, v62, v62
	v_fmac_f32_e32 v105, v64, v64
	v_add_f32_e32 v108, v104, v105
	v_cvt_pk_bf16_f32 v104, v62, v63
	v_cvt_pk_bf16_f32 v105, v64, v65
	s_waitcnt vmcnt(14)
	v_lshlrev_b32_e32 v64, 16, v106
	v_and_b32_e32 v65, 0xffff0000, v106
	v_lshl_add_u64 v[62:63], s[42:43], 0, v[102:103]
	v_pk_add_f32 v[58:59], v[58:59], v[64:65]
	v_lshl_add_u64 v[62:63], v[136:137], 1, v[62:63]
	v_lshlrev_b32_e32 v102, 16, v107
	v_and_b32_e32 v103, 0xffff0000, v107
	v_mul_f32_e32 v64, v59, v59
	v_lshl_add_u64 v[62:63], v[62:63], 0, v[200:201]
	v_mov_b32_e32 v192, v104
	v_mov_b32_e32 v193, v105
	v_pk_add_f32 v[60:61], v[60:61], v[102:103]
	v_fmac_f32_e32 v64, v58, v58
	v_cvt_pk_bf16_f32 v58, v58, v59
	v_cvt_pk_bf16_f32 v59, v60, v61
	v_mul_f32_e32 v65, v61, v61
	v_mov_b32_e32 v194, v58
	v_mov_b32_e32 v195, v59
	s_nop 1
	v_permlane16_swap_b32_e32 v192, v194
	v_permlane16_swap_b32_e32 v193, v195
	global_store_dwordx4 v[62:63], v[192:195], off
	s_waitcnt vmcnt(14)
; __device__ __forceinline__ unsigned cvt_pk_bf16(float lo, float hi) { unsigned r; asm volatile("v_cvt_pk_bf16_f32 %0, %1, %2" : "=v"(r) : "v"(lo), "v"(hi)); return r; }
;     __device__ __forceinline__ void operator()(f32x4 (&acc)[2][2][4][2], const Unit& u, int wr, int wc, int fr, int fq) const {
;     ...
;             for (int m = 0; m < 4; ++m) { const int row = u.pm * BM + ai * HALF + wr * 64 + m * 16 + fr; const size_t off = (size_t)row * ldc + col0; float sq = 0.f;
; #pragma unroll
;                 for (int bj = 0; bj < 2; ++bj)
; #pragma unroll
;                     for (int n = 0; n < 2; ++n) { const unsigned long long b = old[m][bj][n];
;                         const unsigned blo = (unsigned)b, bhi = (unsigned)(b >> 32);
;                         f32x4 v; v[0] = __builtin_bit_cast(float, blo << 16); v[1] = __builtin_bit_cast(float, blo & 0xffff0000u); v[2] = __builtin_bit_cast(float, bhi << 16); v[3] = __builtin_bit_cast(float, bhi & 0xffff0000u);
;                         v = v + acc[ai][bj][m][n];
;                         sq += (v[0] * v[0] + v[1] * v[1]) + (v[2] * v[2] + v[3] * v[3]);
;                         *(unsigned long long*)(xb + off + bj * HALF + n * 16) = (unsigned long long)cvt_pk_bf16(v[0], v[1]) | ((unsigned long long)cvt_pk_bf16(v[2], v[3]) << 32); }
;                 sq += __shfl_xor(sq, 16); sq += __shfl_xor(sq, 32);
;                 if (fq == 0) ssp[(size_t)row * 16 + 4 * u.pn + wc] = sq; }
	v_lshlrev_b32_e32 v58, 16, v100
	v_and_b32_e32 v59, 0xffff0000, v100
	v_fmac_f32_e32 v65, v60, v60
	v_lshlrev_b32_e32 v60, 16, v101
	v_and_b32_e32 v61, 0xffff0000, v101
	v_pk_add_f32 v[54:55], v[54:55], v[58:59]
	v_pk_add_f32 v[56:57], v[56:57], v[60:61]
	v_mul_f32_e32 v58, v55, v55
	v_fmac_f32_e32 v58, v54, v54
	v_mul_f32_e32 v59, v57, v57
	v_cvt_pk_bf16_f32 v54, v54, v55
	v_cvt_pk_bf16_f32 v55, v56, v57
	v_fmac_f32_e32 v59, v56, v56
	v_mov_b32_e32 v196, v54
	v_mov_b32_e32 v197, v55
	s_waitcnt vmcnt(13)
	v_lshlrev_b32_e32 v54, 16, v98
	v_and_b32_e32 v55, 0xffff0000, v98
	v_lshlrev_b32_e32 v56, 16, v99
	v_and_b32_e32 v57, 0xffff0000, v99
	v_pk_add_f32 v[52:53], v[52:53], v[56:57]
	v_pk_add_f32 v[50:51], v[50:51], v[54:55]
	v_add_f32_e32 v64, v64, v65
	v_mul_f32_e32 v54, v51, v51
	v_mul_f32_e32 v55, v53, v53
	v_add_f32_e32 v64, v108, v64
	v_add_f32_e32 v58, v58, v59
	v_fmac_f32_e32 v54, v50, v50
	v_fmac_f32_e32 v55, v52, v52
	v_add_f32_e32 v58, v64, v58
	v_add_f32_e32 v54, v54, v55
	v_add_f32_e32 v54, v58, v54
	v_cvt_pk_bf16_f32 v50, v50, v51
	v_cvt_pk_bf16_f32 v51, v52, v53
	v_mov_b32_e32 v198, v50
	v_mov_b32_e32 v199, v51
	s_nop 1
	v_permlane16_swap_b32_e32 v196, v198
	v_permlane16_swap_b32_e32 v197, v199
	global_store_dwordx4 v[62:63], v[196:199], off offset:256
	ds_bpermute_b32 v50, v114, v54
	s_waitcnt lgkmcnt(0)
	v_add_f32_e32 v50, v54, v50
	ds_bpermute_b32 v51, v115, v50
	s_and_saveexec_b64 s[74:75], s[4:5]
	s_cbranch_execz .LBB0_1525
	v_readlane_b32 s12, v253, 38
	v_lshlrev_b64 v[52:53], 6, v[96:97]
	v_readlane_b32 s13, v253, 39
	s_lshl_b32 s64, s82, 2
	s_waitcnt lgkmcnt(0)
	v_add_f32_e32 v50, v50, v51
	v_lshl_add_u64 v[52:53], s[12:13], 0, v[52:53]
	v_lshl_add_u64 v[52:53], s[72:73], 2, v[52:53]
	v_lshl_add_u64 v[52:53], v[52:53], 0, s[64:65]
	global_store_dword v[52:53], v50, off
.LBB0_1525:
	s_or_b64 exec, exec, s[74:75]
	s_waitcnt vmcnt(13)
	v_lshlrev_b32_e32 v52, 16, v94
	v_and_b32_e32 v53, 0xffff0000, v94
	v_lshlrev_b32_e32 v54, 16, v95
	v_and_b32_e32 v55, 0xffff0000, v95
	v_pk_add_f32 v[48:49], v[48:49], v[54:55]
	v_pk_add_f32 v[46:47], v[46:47], v[52:53]
	s_waitcnt lgkmcnt(0)
	v_lshlrev_b64 v[50:51], 10, v[84:85]
	v_mul_f32_e32 v52, v47, v47
	v_mul_f32_e32 v53, v49, v49
	v_fmac_f32_e32 v52, v46, v46
	v_fmac_f32_e32 v53, v48, v48
	v_cvt_pk_bf16_f32 v46, v46, v47
	v_cvt_pk_bf16_f32 v47, v48, v49
	v_lshl_add_u64 v[48:49], v[50:51], 1, s[42:43]
	v_lshl_add_u64 v[48:49], v[136:137], 1, v[48:49]
	v_lshl_add_u64 v[48:49], v[48:49], 0, v[200:201]
	v_mov_b32_e32 v192, v46
	v_mov_b32_e32 v193, v47
	s_waitcnt vmcnt(12)
	v_lshlrev_b32_e32 v46, 16, v92
	v_and_b32_e32 v47, 0xffff0000, v92
	v_lshlrev_b32_e32 v50, 16, v93
	v_and_b32_e32 v51, 0xffff0000, v93
	v_pk_add_f32 v[44:45], v[44:45], v[50:51]
	v_pk_add_f32 v[42:43], v[42:43], v[46:47]
	v_mul_f32_e32 v47, v45, v45
	v_mul_f32_e32 v46, v43, v43
	v_fmac_f32_e32 v46, v42, v42
	v_fmac_f32_e32 v47, v44, v44
	v_add_f32_e32 v52, v52, v53
	v_add_f32_e32 v46, v46, v47
	v_add_f32_e32 v52, v52, v46
	s_waitcnt vmcnt(11)
	v_lshlrev_b32_e32 v46, 16, v90
	v_and_b32_e32 v47, 0xffff0000, v90
	v_lshlrev_b32_e32 v50, 16, v91
	v_and_b32_e32 v51, 0xffff0000, v91
	v_pk_add_f32 v[40:41], v[40:41], v[50:51]
	v_pk_add_f32 v[38:39], v[38:39], v[46:47]
	v_cvt_pk_bf16_f32 v42, v42, v43
	v_mul_f32_e32 v46, v41, v41
	v_mul_f32_e32 v43, v39, v39
	v_fmac_f32_e32 v43, v38, v38
	v_fmac_f32_e32 v46, v40, v40
	v_add_f32_e32 v43, v43, v46
	s_waitcnt vmcnt(10)
	v_lshlrev_b32_e32 v46, 16, v88
	v_and_b32_e32 v47, 0xffff0000, v88
	v_lshlrev_b32_e32 v50, 16, v89
	v_and_b32_e32 v51, 0xffff0000, v89
	v_pk_add_f32 v[36:37], v[36:37], v[50:51]
	v_pk_add_f32 v[46:47], v[34:35], v[46:47]
	v_mul_f32_e32 v35, v37, v37
	v_mul_f32_e32 v34, v47, v47
	v_fmac_f32_e32 v34, v46, v46
	v_fmac_f32_e32 v35, v36, v36
	v_add_f32_e32 v43, v52, v43
	v_add_f32_e32 v34, v34, v35
	v_add_f32_e32 v34, v43, v34
	v_mov_b32_e32 v35, v34
	s_nop 1
	v_permlane16_swap_b32_e32 v35, v34
	v_cvt_pk_bf16_f32 v43, v44, v45
	v_mov_b32_e32 v194, v42
	v_mov_b32_e32 v195, v43
	s_nop 1
	v_permlane16_swap_b32_e32 v192, v194
	v_permlane16_swap_b32_e32 v193, v195
	global_store_dwordx4 v[48:49], v[192:195], off
	v_cvt_pk_bf16_f32 v38, v38, v39
	v_cvt_pk_bf16_f32 v39, v40, v41
	s_waitcnt lgkmcnt(0)
	v_add_f32_e32 v34, v34, v35
	ds_bpermute_b32 v35, v115, v34
	v_mov_b32_e32 v196, v38
	v_mov_b32_e32 v197, v39
	v_cvt_pk_bf16_f32 v38, v46, v47
	v_cvt_pk_bf16_f32 v39, v36, v37
	v_mov_b32_e32 v198, v38
	v_mov_b32_e32 v199, v39
	s_nop 1
	v_permlane16_swap_b32_e32 v196, v198
	v_permlane16_swap_b32_e32 v197, v199
	global_store_dwordx4 v[48:49], v[196:199], off offset:256
	s_and_saveexec_b64 s[74:75], s[4:5]
	s_cbranch_execz .LBB0_1527
	v_readlane_b32 s12, v253, 38
	v_lshlrev_b64 v[36:37], 6, v[84:85]
	v_readlane_b32 s13, v253, 39
	s_lshl_b32 s64, s82, 2
	s_waitcnt lgkmcnt(0)
	v_add_f32_e32 v34, v34, v35
	v_lshl_add_u64 v[36:37], s[12:13], 0, v[36:37]
	v_lshl_add_u64 v[36:37], s[72:73], 2, v[36:37]
	v_lshl_add_u64 v[36:37], v[36:37], 0, s[64:65]
	global_store_dword v[36:37], v34, off
; __device__ __forceinline__ unsigned cvt_pk_bf16(float lo, float hi) { unsigned r; asm volatile("v_cvt_pk_bf16_f32 %0, %1, %2" : "=v"(r) : "v"(lo), "v"(hi)); return r; }
;     __device__ __forceinline__ void operator()(f32x4 (&acc)[2][2][4][2], const Unit& u, int wr, int wc, int fr, int fq) const {
;     ...
;             for (int m = 0; m < 4; ++m) { const int row = u.pm * BM + ai * HALF + wr * 64 + m * 16 + fr; const size_t off = (size_t)row * ldc + col0; float sq = 0.f;
; #pragma unroll
;                 for (int bj = 0; bj < 2; ++bj)
; #pragma unroll
;                     for (int n = 0; n < 2; ++n) { const unsigned long long b = old[m][bj][n];
;                         const unsigned blo = (unsigned)b, bhi = (unsigned)(b >> 32);
;                         f32x4 v; v[0] = __builtin_bit_cast(float, blo << 16); v[1] = __builtin_bit_cast(float, blo & 0xffff0000u); v[2] = __builtin_bit_cast(float, bhi << 16); v[3] = __builtin_bit_cast(float, bhi & 0xffff0000u);
;                         v = v + acc[ai][bj][m][n];
;                         sq += (v[0] * v[0] + v[1] * v[1]) + (v[2] * v[2] + v[3] * v[3]);
;                         *(unsigned long long*)(xb + off + bj * HALF + n * 16) = (unsigned long long)cvt_pk_bf16(v[0], v[1]) | ((unsigned long long)cvt_pk_bf16(v[2], v[3]) << 32); }
;                 sq += __shfl_xor(sq, 16); sq += __shfl_xor(sq, 32);
;                 if (fq == 0) ssp[(size_t)row * 16 + 4 * u.pn + wc] = sq; }
.LBB0_1527:
	s_or_b64 exec, exec, s[74:75]
	s_waitcnt vmcnt(11)
	v_lshlrev_b32_e32 v36, 16, v86
	v_and_b32_e32 v37, 0xffff0000, v86
	v_lshlrev_b32_e32 v38, 16, v87
	v_and_b32_e32 v39, 0xffff0000, v87
	v_pk_add_f32 v[32:33], v[32:33], v[38:39]
	v_pk_add_f32 v[30:31], v[30:31], v[36:37]
	s_waitcnt lgkmcnt(0)
	v_lshlrev_b64 v[34:35], 10, v[70:71]
	v_mul_f32_e32 v36, v31, v31
	v_mul_f32_e32 v37, v33, v33
	v_fmac_f32_e32 v36, v30, v30
	v_fmac_f32_e32 v37, v32, v32
	v_cvt_pk_bf16_f32 v30, v30, v31
	v_cvt_pk_bf16_f32 v31, v32, v33
	v_lshl_add_u64 v[32:33], v[34:35], 1, s[42:43]
	v_lshl_add_u64 v[32:33], v[136:137], 1, v[32:33]
	v_lshl_add_u64 v[32:33], v[32:33], 0, v[200:201]
	v_mov_b32_e32 v192, v30
	v_mov_b32_e32 v193, v31
	s_waitcnt vmcnt(10)
	v_lshlrev_b32_e32 v30, 16, v82
	v_and_b32_e32 v31, 0xffff0000, v82
	v_lshlrev_b32_e32 v34, 16, v83
	v_and_b32_e32 v35, 0xffff0000, v83
	v_pk_add_f32 v[28:29], v[28:29], v[34:35]
	v_pk_add_f32 v[26:27], v[26:27], v[30:31]
	v_mul_f32_e32 v31, v29, v29
	v_mul_f32_e32 v30, v27, v27
	v_fmac_f32_e32 v30, v26, v26
	v_fmac_f32_e32 v31, v28, v28
	v_add_f32_e32 v36, v36, v37
	v_add_f32_e32 v30, v30, v31
	v_add_f32_e32 v36, v36, v30
	s_waitcnt vmcnt(9)
	v_lshlrev_b32_e32 v30, 16, v78
	v_and_b32_e32 v31, 0xffff0000, v78
	v_lshlrev_b32_e32 v34, 16, v79
	v_and_b32_e32 v35, 0xffff0000, v79
	v_pk_add_f32 v[24:25], v[24:25], v[34:35]
	v_pk_add_f32 v[22:23], v[22:23], v[30:31]
	v_cvt_pk_bf16_f32 v26, v26, v27
	v_mul_f32_e32 v30, v25, v25
	v_mul_f32_e32 v27, v23, v23
	v_fmac_f32_e32 v27, v22, v22
	v_fmac_f32_e32 v30, v24, v24
	v_add_f32_e32 v27, v27, v30
	s_waitcnt vmcnt(8)
	v_lshlrev_b32_e32 v30, 16, v74
	v_and_b32_e32 v31, 0xffff0000, v74
	v_lshlrev_b32_e32 v34, 16, v75
	v_and_b32_e32 v35, 0xffff0000, v75
	v_pk_add_f32 v[20:21], v[20:21], v[34:35]
	v_pk_add_f32 v[30:31], v[18:19], v[30:31]
	v_mul_f32_e32 v19, v21, v21
	v_mul_f32_e32 v18, v31, v31
	v_fmac_f32_e32 v18, v30, v30
	v_fmac_f32_e32 v19, v20, v20
	v_add_f32_e32 v27, v36, v27
	v_add_f32_e32 v18, v18, v19
	v_add_f32_e32 v18, v27, v18
	v_mov_b32_e32 v19, v18
	s_nop 1
	v_permlane16_swap_b32_e32 v19, v18
	v_cvt_pk_bf16_f32 v27, v28, v29
	v_mov_b32_e32 v194, v26
	v_mov_b32_e32 v195, v27
	s_nop 1
	v_permlane16_swap_b32_e32 v192, v194
	v_permlane16_swap_b32_e32 v193, v195
	global_store_dwordx4 v[32:33], v[192:195], off
	v_cvt_pk_bf16_f32 v22, v22, v23
	v_cvt_pk_bf16_f32 v23, v24, v25
	s_waitcnt lgkmcnt(0)
	v_add_f32_e32 v18, v18, v19
	ds_bpermute_b32 v19, v115, v18
	v_mov_b32_e32 v196, v22
	v_mov_b32_e32 v197, v23
	v_cvt_pk_bf16_f32 v22, v30, v31
	v_cvt_pk_bf16_f32 v23, v20, v21
	v_mov_b32_e32 v198, v22
	v_mov_b32_e32 v199, v23
	s_nop 1
	v_permlane16_swap_b32_e32 v196, v198
	v_permlane16_swap_b32_e32 v197, v199
	global_store_dwordx4 v[32:33], v[196:199], off offset:256
	s_and_saveexec_b64 s[74:75], s[4:5]
	s_cbranch_execz .LBB0_1529
	v_readlane_b32 s12, v253, 38
	v_lshlrev_b64 v[20:21], 6, v[70:71]
	v_readlane_b32 s13, v253, 39
	s_lshl_b32 s64, s82, 2
	s_waitcnt lgkmcnt(0)
	v_add_f32_e32 v18, v18, v19
	v_lshl_add_u64 v[20:21], s[12:13], 0, v[20:21]
	v_lshl_add_u64 v[20:21], s[72:73], 2, v[20:21]
	v_lshl_add_u64 v[20:21], v[20:21], 0, s[64:65]
	global_store_dword v[20:21], v18, off
.LBB0_1529:
	s_or_b64 exec, exec, s[74:75]
	s_waitcnt vmcnt(9)
	v_lshlrev_b32_e32 v20, 16, v80
	v_and_b32_e32 v21, 0xffff0000, v80
	v_lshlrev_b32_e32 v22, 16, v81
	v_and_b32_e32 v23, 0xffff0000, v81
	v_pk_add_f32 v[16:17], v[16:17], v[22:23]
	v_pk_add_f32 v[14:15], v[14:15], v[20:21]
	s_waitcnt lgkmcnt(0)
	v_lshlrev_b64 v[18:19], 10, v[66:67]
	v_mul_f32_e32 v20, v15, v15
	v_mul_f32_e32 v21, v17, v17
	v_fmac_f32_e32 v20, v14, v14
	v_fmac_f32_e32 v21, v16, v16
	v_cvt_pk_bf16_f32 v14, v14, v15
	v_cvt_pk_bf16_f32 v15, v16, v17
	v_lshl_add_u64 v[16:17], v[18:19], 1, s[42:43]
	v_lshl_add_u64 v[16:17], v[136:137], 1, v[16:17]
	v_lshl_add_u64 v[16:17], v[16:17], 0, v[200:201]
	v_mov_b32_e32 v192, v14
	v_mov_b32_e32 v193, v15
	s_waitcnt vmcnt(9)
	v_lshlrev_b32_e32 v14, 16, v76
	v_and_b32_e32 v15, 0xffff0000, v76
	v_lshlrev_b32_e32 v18, 16, v77
	v_and_b32_e32 v19, 0xffff0000, v77
	v_pk_add_f32 v[12:13], v[12:13], v[18:19]
	v_pk_add_f32 v[10:11], v[10:11], v[14:15]
	v_mul_f32_e32 v15, v13, v13
	v_mul_f32_e32 v14, v11, v11
	v_fmac_f32_e32 v14, v10, v10
	v_fmac_f32_e32 v15, v12, v12
	v_add_f32_e32 v20, v20, v21
	v_add_f32_e32 v14, v14, v15
	v_add_f32_e32 v20, v20, v14
	s_waitcnt vmcnt(8)
	v_lshlrev_b32_e32 v14, 16, v72
	v_and_b32_e32 v15, 0xffff0000, v72
	v_lshlrev_b32_e32 v18, 16, v73
	v_and_b32_e32 v19, 0xffff0000, v73
	v_pk_add_f32 v[8:9], v[8:9], v[18:19]
	v_pk_add_f32 v[6:7], v[6:7], v[14:15]
	v_cvt_pk_bf16_f32 v10, v10, v11
	v_mul_f32_e32 v14, v9, v9
	v_mul_f32_e32 v11, v7, v7
	v_fmac_f32_e32 v11, v6, v6
	v_fmac_f32_e32 v14, v8, v8
	v_add_f32_e32 v11, v11, v14
	s_waitcnt vmcnt(8)
	v_lshlrev_b32_e32 v14, 16, v68
	v_and_b32_e32 v15, 0xffff0000, v68
	v_lshlrev_b32_e32 v18, 16, v69
	v_and_b32_e32 v19, 0xffff0000, v69
	v_pk_add_f32 v[4:5], v[4:5], v[18:19]
	v_pk_add_f32 v[14:15], v[2:3], v[14:15]
	v_mul_f32_e32 v3, v5, v5
	v_mul_f32_e32 v2, v15, v15
	v_fmac_f32_e32 v2, v14, v14
	v_fmac_f32_e32 v3, v4, v4
	v_add_f32_e32 v11, v20, v11
	v_add_f32_e32 v2, v2, v3
	v_add_f32_e32 v2, v11, v2
	v_mov_b32_e32 v3, v2
	s_nop 1
	v_permlane16_swap_b32_e32 v3, v2
	v_cvt_pk_bf16_f32 v11, v12, v13
	v_mov_b32_e32 v194, v10
	v_mov_b32_e32 v195, v11
	s_nop 1
	v_permlane16_swap_b32_e32 v192, v194
	v_permlane16_swap_b32_e32 v193, v195
	global_store_dwordx4 v[16:17], v[192:195], off
	v_cvt_pk_bf16_f32 v6, v6, v7
	v_cvt_pk_bf16_f32 v7, v8, v9
	s_waitcnt lgkmcnt(0)
	v_add_f32_e32 v2, v2, v3
	ds_bpermute_b32 v3, v115, v2
	v_mov_b32_e32 v196, v6
	v_mov_b32_e32 v197, v7
	v_cvt_pk_bf16_f32 v6, v14, v15
	v_cvt_pk_bf16_f32 v7, v4, v5
	v_mov_b32_e32 v198, v6
	v_mov_b32_e32 v199, v7
	s_nop 1
	v_permlane16_swap_b32_e32 v196, v198
	v_permlane16_swap_b32_e32 v197, v199
	global_store_dwordx4 v[16:17], v[196:199], off offset:256
	s_and_saveexec_b64 s[74:75], s[4:5]
	s_cbranch_execz .LBB0_1531
	v_readlane_b32 s12, v253, 38
	v_lshlrev_b64 v[4:5], 6, v[66:67]
	v_readlane_b32 s13, v253, 39
	s_lshl_b32 s64, s82, 2
	s_waitcnt lgkmcnt(0)
	v_add_f32_e32 v2, v2, v3
	v_lshl_add_u64 v[4:5], s[12:13], 0, v[4:5]
	v_lshl_add_u64 v[4:5], s[72:73], 2, v[4:5]
	v_lshl_add_u64 v[4:5], v[4:5], 0, s[64:65]
	global_store_dword v[4:5], v2, off
